# adds early issue of the per-head a_log/dt_bias loads in gdn_prep
# speedup vs baseline: 1.0112x; 1.0112x over previous
; #define LAS __attribute__((address_space(3)))
; DI float bflo(unsigned w) { return __uint_as_float(w << 16); }
; DI float bfhi(unsigned w) { return __uint_as_float(w & 0xffff0000u); }
; DI float bf2f(bf16_t u) { return __uint_as_float(((unsigned)u) << 16); }
; DI float silu_f(float g) { return g * frcp(1.f + fexp2(-1.4426950408889634f * g)); }
;     ...
;     for (int which = 0; which < 3; ++which) {
;         const int t = tid >> 3, cg8 = tid & 7; const int col = which * 512 + h * 64 + cg8 * 8;
;         float acc[8];
; #pragma unroll
;         for (int e = 0; e < 8; ++e) acc[e] = 0.f;
; #pragma unroll
;         for (int j = 0; j < 4; ++j) { const int sp = n * 64 + t - 3 + j; const float ok = sp >= 0 ? 1.f : 0.f;
;             const u32x4 xv = xin[which * 4 + j];
;             const f32x4 w0 = *(const f32x4*)(conv_w + j * 1536 + col) * ok, w1 = *(const f32x4*)(conv_w + j * 1536 + col + 4) * ok;
;             acc[0] += w0[0] * bflo(xv.x); acc[1] += w0[1] * bfhi(xv.x); acc[2] += w0[2] * bflo(xv.y); acc[3] += w0[3] * bfhi(xv.y);
;             acc[4] += w1[0] * bflo(xv.z); acc[5] += w1[1] * bfhi(xv.z); acc[6] += w1[2] * bflo(xv.w); acc[7] += w1[3] * bfhi(xv.w); }
; #pragma unroll
;         for (int e = 0; e < 8; ++e) acc[e] = silu_f(acc[e]);
;         if (which == 2) { LAS float* dst = vc + t * 68 + cg8 * 8; *(LAS f32x4*)dst = (f32x4){acc[0], acc[1], acc[2], acc[3]}; *(LAS f32x4*)(dst + 4) = (f32x4){acc[4], acc[5], acc[6], acc[7]}; }
;         else {
;             float ss = (acc[0] * acc[0] + acc[1] * acc[1]) + (acc[2] * acc[2] + acc[3] * acc[3]) + (acc[4] * acc[4] + acc[5] * acc[5]) + (acc[6] * acc[6] + acc[7] * acc[7]);
;             ss += __shfl_xor(ss, 1); ss += __shfl_xor(ss, 2); ss += __shfl_xor(ss, 4);
;             const float sc = (which ? 1.0f : 0.125f) * __builtin_amdgcn_rsqf(ss + 1e-6f);
;             const f32x4 y0 = (f32x4){acc[0], acc[1], acc[2], acc[3]} * sc, y1 = (f32x4){acc[4], acc[5], acc[6], acc[7]} * sc;
;             LAS float* dst = (which ? kc : qc) + t * 68 + cg8 * 8; *(LAS f32x4*)dst = y0; *(LAS f32x4*)(dst + 4) = y1;
;     ...
;     { const float ga = bf2f(gain), gb = bf2f(gbin);
;         const float x = ga + dt_bias[h]; const float sp = fmaxf(x, 0.f) + log1pf(expf(-fabsf(x)));
;         float gv = -expf(a_log[h]) * sp; const float bv = 1.f / (1.f + expf(-gb));
.LBB0_434:
	s_lshl_b32 s19, s2, 6
	s_and_b32 s19, s19, 0xfc0
	v_add_u32_e32 v2, s19, v110
	v_cmp_lt_u32_e32 vcc, 2, v2
	s_bfe_u32 s3, s2, 0x30006
	s_bfe_u32 s100, s70, 0x30006
	s_xor_b32 s100, s100, s3
	s_mul_i32 s100, s100, 0x300
	v_lshlrev_b32_e32 v255, 2, v111
	v_add_u32_e32 v255, s100, v255
	v_add_u32_e32 v255, 0x24100, v255
	s_movk_i32 s19, 0x1000
	v_cndmask_b32_e64 v26, 0, 1.0, vcc
	v_cmp_lt_u32_e32 vcc, 1, v2
	s_mov_b64 s[42:43], 0x1800
	s_waitcnt vmcnt(0)
	s_lshl_b32 s101, s3, 2
	v_mov_b32_e32 v254, s101
	v_readlane_b32 s100, v247, 9
	v_readlane_b32 s101, v247, 10
	global_load_dword v252, v254, s[50:51]
	s_nop 4
	global_load_dword v253, v254, s[100:101]
	v_lshlrev_b32_e32 v208, 16, v54
	v_cndmask_b32_e64 v24, 0, 1.0, vcc
	v_cmp_eq_u32_e32 vcc, 0, v2
	v_lshlrev_b32_e32 v2, 2, v111
	v_lshl_or_b32 v82, s3, 8, v2
	ds_read_b128 v[18:21], v255 offset:0
	ds_read_b128 v[2:5], v255 offset:16
	v_lshl_add_u64 v[14:15], s[48:49], 0, v[82:83]
	v_cndmask_b32_e64 v22, 1.0, 0, vcc
	v_and_b32_e32 v209, 0xffff0000, v54
	s_waitcnt lgkmcnt(0)
	v_pk_mul_f32 v[18:19], v[26:27], v[18:19] op_sel_hi:[0,1]
	s_waitcnt lgkmcnt(0)
	v_pk_mul_f32 v[10:11], v[2:3], v[26:27] op_sel_hi:[1,0]
	v_add_co_u32_e32 v2, vcc, s19, v14
	v_pk_mul_f32 v[8:9], v[4:5], v[26:27] op_sel_hi:[1,0]
	v_lshl_add_u64 v[4:5], v[14:15], 0, s[42:43]
	v_addc_co_u32_e32 v3, vcc, 0, v15, vcc
	ds_read_b128 v[28:31], v255 offset:768
	s_nop 0
	ds_read_b128 v[4:7], v255 offset:784
	s_movk_i32 s19, 0x3000
	s_mov_b64 s[42:43], 0x3000
	v_lshl_add_u64 v[32:33], v[14:15], 0, s[42:43]
	s_mov_b64 s[42:43], 0x4800
	v_lshl_add_u64 v[200:201], v[14:15], 0, s[42:43]
	v_pk_mul_f32 v[20:21], v[26:27], v[20:21] op_sel_hi:[0,1]
	s_mov_b64 s[42:43], 0x2000
	s_waitcnt lgkmcnt(0)
	v_pk_mul_f32 v[28:29], v[24:25], v[28:29] op_sel_hi:[0,1]
	s_waitcnt lgkmcnt(0)
	v_pk_mul_f32 v[12:13], v[6:7], v[24:25] op_sel_hi:[1,0]
	v_add_co_u32_e32 v6, vcc, s19, v14
	s_movk_i32 s19, 0x4000
	s_nop 0
	v_addc_co_u32_e32 v7, vcc, 0, v15, vcc
	v_pk_mul_f32 v[16:17], v[4:5], v[24:25] op_sel_hi:[1,0]
	v_add_co_u32_e32 v4, vcc, s19, v14
	v_pk_mul_f32 v[30:31], v[24:25], v[30:31] op_sel_hi:[0,1]
	s_nop 0
	v_addc_co_u32_e32 v5, vcc, 0, v15, vcc
	ds_read_b128 v[94:97], v255 offset:1536
	ds_read_b128 v[196:199], v255 offset:1552
	s_movk_i32 s19, 0x2000
	s_waitcnt lgkmcnt(0)
	v_pk_mul_f32 v[94:95], v[22:23], v[94:95] op_sel_hi:[0,1]
	s_waitcnt lgkmcnt(0)
	v_pk_mul_f32 v[32:33], v[198:199], v[22:23] op_sel_hi:[1,0]
	v_pk_mul_f32 v[98:99], v[196:197], v[22:23] op_sel_hi:[1,0]
	ds_read_b128 v[196:199], v255 offset:2304
	ds_read_b128 v[204:207], v255 offset:2320
	v_lshlrev_b32_e32 v200, 16, v70
	v_and_b32_e32 v201, 0xffff0000, v70
	v_pk_fma_f32 v[18:19], v[18:19], v[200:201], 0 op_sel_hi:[1,1,0]
	v_lshlrev_b32_e32 v200, 16, v74
	v_and_b32_e32 v201, 0xffff0000, v74
	v_pk_fma_f32 v[18:19], v[28:29], v[200:201], v[18:19]
	v_lshlrev_b32_e32 v28, 16, v58
	v_and_b32_e32 v29, 0xffff0000, v58
	v_pk_fma_f32 v[18:19], v[94:95], v[28:29], v[18:19]
	v_lshlrev_b32_e32 v28, 16, v78
	v_and_b32_e32 v29, 0xffff0000, v78
	v_pk_mul_f32 v[96:97], v[22:23], v[96:97] op_sel_hi:[0,1]
	s_waitcnt lgkmcnt(0)
	v_pk_fma_f32 v[18:19], v[196:197], v[28:29], v[18:19]
	s_nop 0
	v_mul_f32_e32 v23, 0xbfb8aa3b, v18
	v_exp_f32_e32 v23, v23
	s_nop 0
	v_add_f32_e32 v23, 1.0, v23
	v_rcp_f32_e32 v28, v23
	v_mul_f32_e32 v23, 0xbfb8aa3b, v19
	v_exp_f32_e32 v23, v23
	s_nop 0
	v_add_f32_e32 v23, 1.0, v23
	v_rcp_f32_e32 v29, v23
	s_nop 0
	v_pk_mul_f32 v[28:29], v[18:19], v[28:29]
	v_lshlrev_b32_e32 v18, 16, v71
	v_and_b32_e32 v19, 0xffff0000, v71
	v_pk_fma_f32 v[18:19], v[20:21], v[18:19], 0 op_sel_hi:[1,1,0]
	v_lshlrev_b32_e32 v20, 16, v75
	v_and_b32_e32 v21, 0xffff0000, v75
	v_pk_fma_f32 v[18:19], v[30:31], v[20:21], v[18:19]
	v_lshlrev_b32_e32 v20, 16, v59
	v_and_b32_e32 v21, 0xffff0000, v59
	v_pk_fma_f32 v[18:19], v[96:97], v[20:21], v[18:19]
	v_lshlrev_b32_e32 v20, 16, v79
	v_and_b32_e32 v21, 0xffff0000, v79
	v_pk_fma_f32 v[18:19], v[198:199], v[20:21], v[18:19]
	s_nop 0
	v_mul_f32_e32 v20, 0xbfb8aa3b, v18
	v_mul_f32_e32 v21, 0xbfb8aa3b, v19
	v_exp_f32_e32 v20, v20
	v_exp_f32_e32 v21, v21
	v_add_f32_e32 v20, 1.0, v20
	v_add_f32_e32 v21, 1.0, v21
	v_rcp_f32_e32 v20, v20
	v_rcp_f32_e32 v21, v21
	s_nop 0
	v_pk_mul_f32 v[20:21], v[18:19], v[20:21]
	v_lshlrev_b32_e32 v18, 16, v72
	v_and_b32_e32 v19, 0xffff0000, v72
	v_pk_fma_f32 v[10:11], v[10:11], v[18:19], 0 op_sel_hi:[1,1,0]
	v_lshlrev_b32_e32 v18, 16, v76
	v_and_b32_e32 v19, 0xffff0000, v76
	v_pk_fma_f32 v[10:11], v[16:17], v[18:19], v[10:11]
	v_lshlrev_b32_e32 v16, 16, v60
	v_and_b32_e32 v17, 0xffff0000, v60
	v_pk_fma_f32 v[10:11], v[98:99], v[16:17], v[10:11]
	v_lshlrev_b32_e32 v16, 16, v80
	v_and_b32_e32 v17, 0xffff0000, v80
	s_waitcnt lgkmcnt(0)
	v_pk_fma_f32 v[10:11], v[204:205], v[16:17], v[10:11]
	v_add_co_u32_e32 v98, vcc, s19, v14
	v_mul_f32_e32 v16, 0xbfb8aa3b, v10
	v_mul_f32_e32 v17, 0xbfb8aa3b, v11
	v_exp_f32_e32 v16, v16
	v_exp_f32_e32 v17, v17
	v_addc_co_u32_e32 v99, vcc, 0, v15, vcc
	v_add_f32_e32 v16, 1.0, v16
	v_add_f32_e32 v17, 1.0, v17
	v_rcp_f32_e32 v16, v16
	v_rcp_f32_e32 v17, v17
	s_movk_i32 s19, 0x5000
	v_pk_mul_f32 v[30:31], v[10:11], v[16:17]
	v_lshlrev_b32_e32 v10, 16, v73
	v_and_b32_e32 v11, 0xffff0000, v73
	v_pk_fma_f32 v[8:9], v[8:9], v[10:11], 0 op_sel_hi:[1,1,0]
	v_lshlrev_b32_e32 v10, 16, v77
	v_and_b32_e32 v11, 0xffff0000, v77
	v_pk_fma_f32 v[8:9], v[12:13], v[10:11], v[8:9]
	v_lshlrev_b32_e32 v10, 16, v61
	v_and_b32_e32 v11, 0xffff0000, v61
	v_pk_fma_f32 v[8:9], v[32:33], v[10:11], v[8:9]
	v_lshlrev_b32_e32 v10, 16, v81
	v_and_b32_e32 v11, 0xffff0000, v81
	v_pk_fma_f32 v[8:9], v[206:207], v[10:11], v[8:9]
	v_mov_b32_e32 v17, v31
	v_mul_f32_e32 v10, 0xbfb8aa3b, v9
	v_exp_f32_e32 v10, v10
	s_nop 0
	v_add_f32_e32 v10, 1.0, v10
	v_rcp_f32_e32 v11, v10
	v_mul_f32_e32 v10, 0xbfb8aa3b, v8
	v_exp_f32_e32 v10, v10
	s_nop 0
	v_add_f32_e32 v10, 1.0, v10
	v_rcp_f32_e32 v10, v10
	s_nop 0
	v_pk_mul_f32 v[12:13], v[8:9], v[10:11]
	v_mov_b32_e32 v10, v29
	v_mov_b32_e32 v11, v21
	v_mov_b32_e32 v8, v28
	v_mov_b32_e32 v9, v20
	v_pk_mul_f32 v[10:11], v[10:11], v[10:11]
	v_mov_b32_e32 v16, v13
	v_pk_fma_f32 v[8:9], v[8:9], v[8:9], v[10:11]
	v_mov_b32_e32 v10, v12
	v_mov_b32_e32 v11, v30
	v_pk_mul_f32 v[16:17], v[16:17], v[16:17]
	v_add_f32_e32 v8, v8, v9
	v_pk_fma_f32 v[10:11], v[10:11], v[10:11], v[16:17]
	s_nop 0
	v_add_f32_e32 v8, v11, v8
	v_add_f32_e32 v8, v10, v8
	ds_bpermute_b32 v9, v101, v8
	s_waitcnt lgkmcnt(0)
; #define LAS __attribute__((address_space(3)))
; DI float bflo(unsigned w) { return __uint_as_float(w << 16); }
; DI float bfhi(unsigned w) { return __uint_as_float(w & 0xffff0000u); }
;     ...
;     for (int which = 0; which < 3; ++which) {
;         const int t = tid >> 3, cg8 = tid & 7; const int col = which * 512 + h * 64 + cg8 * 8;
;         float acc[8];
; #pragma unroll
;         for (int e = 0; e < 8; ++e) acc[e] = 0.f;
; #pragma unroll
;         for (int j = 0; j < 4; ++j) { const int sp = n * 64 + t - 3 + j; const float ok = sp >= 0 ? 1.f : 0.f;
;             const u32x4 xv = xin[which * 4 + j];
;             const f32x4 w0 = *(const f32x4*)(conv_w + j * 1536 + col) * ok, w1 = *(const f32x4*)(conv_w + j * 1536 + col + 4) * ok;
;             acc[0] += w0[0] * bflo(xv.x); acc[1] += w0[1] * bfhi(xv.x); acc[2] += w0[2] * bflo(xv.y); acc[3] += w0[3] * bfhi(xv.y);
;             acc[4] += w1[0] * bflo(xv.z); acc[5] += w1[1] * bfhi(xv.z); acc[6] += w1[2] * bflo(xv.w); acc[7] += w1[3] * bfhi(xv.w); }
; #pragma unroll
;         for (int e = 0; e < 8; ++e) acc[e] = silu_f(acc[e]);
;         if (which == 2) { LAS float* dst = vc + t * 68 + cg8 * 8; *(LAS f32x4*)dst = (f32x4){acc[0], acc[1], acc[2], acc[3]}; *(LAS f32x4*)(dst + 4) = (f32x4){acc[4], acc[5], acc[6], acc[7]}; }
;         else {
;             float ss = (acc[0] * acc[0] + acc[1] * acc[1]) + (acc[2] * acc[2] + acc[3] * acc[3]) + (acc[4] * acc[4] + acc[5] * acc[5]) + (acc[6] * acc[6] + acc[7] * acc[7]);
;             ss += __shfl_xor(ss, 1); ss += __shfl_xor(ss, 2); ss += __shfl_xor(ss, 4);
;             const float sc = (which ? 1.0f : 0.125f) * __builtin_amdgcn_rsqf(ss + 1e-6f);
;             const f32x4 y0 = (f32x4){acc[0], acc[1], acc[2], acc[3]} * sc, y1 = (f32x4){acc[4], acc[5], acc[6], acc[7]} * sc;
;             LAS float* dst = (which ? kc : qc) + t * 68 + cg8 * 8; *(LAS f32x4*)dst = y0; *(LAS f32x4*)(dst + 4) = y1;
;             u32x4 hh; hh.x = pk2(y0[0], y0[1]); hh.y = pk2(y0[2], y0[3]); hh.z = pk2(y1[0], y1[1]); hh.w = pk2(y1[2], y1[3]);
;             u32x4 lo; lo.x = pk2(y0[0] - bflo(hh.x), y0[1] - bfhi(hh.x)); lo.y = pk2(y0[2] - bflo(hh.y), y0[3] - bfhi(hh.y)); lo.z = pk2(y1[0] - bflo(hh.z), y1[1] - bfhi(hh.z)); lo.w = pk2(y1[2] - bflo(hh.w), y1[3] - bfhi(hh.w));
;             *(LAS u32x4*)((which ? KH : QH) + t * 72 + cg8 * 8) = hh; *(LAS u32x4*)((which ? KL : QL) + t * 72 + cg8 * 8) = lo; }
	v_add_f32_e32 v8, v8, v9
	ds_bpermute_b32 v9, v102, v8
	s_waitcnt lgkmcnt(0)
	v_add_f32_e32 v8, v8, v9
	ds_bpermute_b32 v9, v103, v8
	s_waitcnt lgkmcnt(0)
	v_add_f32_e32 v8, v8, v9
	v_add_f32_e32 v8, 0x358637bd, v8
	v_rsq_f32_e32 v8, v8
	s_nop 0
	v_mul_f32_e32 v32, 0x3e000000, v8
	v_pk_mul_f32 v[10:11], v[20:21], v[32:33] op_sel_hi:[1,0]
	v_pk_mul_f32 v[8:9], v[28:29], v[32:33] op_sel_hi:[1,0]
	v_pk_mul_f32 v[18:19], v[12:13], v[32:33] op_sel_hi:[1,0]
	v_pk_mul_f32 v[16:17], v[30:31], v[32:33] op_sel_hi:[1,0]
	ds_write_b128 v112, v[8:11]
	ds_write_b128 v112, v[16:19] offset:16
	v_cvt_pk_bf16_f32 v8, v8, v9
	v_cvt_pk_bf16_f32 v9, v10, v11
	v_cvt_pk_bf16_f32 v10, v16, v17
	v_cvt_pk_bf16_f32 v11, v18, v19
	v_lshlrev_b32_e32 v16, 16, v8
	v_and_b32_e32 v17, 0xffff0000, v8
	v_lshlrev_b32_e32 v18, 16, v9
	v_and_b32_e32 v19, 0xffff0000, v9
	v_pk_fma_f32 v[16:17], v[28:29], v[32:33], v[16:17] op_sel_hi:[1,0,1] neg_lo:[0,0,1] neg_hi:[0,0,1]
	v_pk_fma_f32 v[18:19], v[20:21], v[32:33], v[18:19] op_sel_hi:[1,0,1] neg_lo:[0,0,1] neg_hi:[0,0,1]
	v_cvt_pk_bf16_f32 v16, v16, v17
	v_cvt_pk_bf16_f32 v17, v18, v19
	v_lshlrev_b32_e32 v18, 16, v10
	v_and_b32_e32 v19, 0xffff0000, v10
	v_lshlrev_b32_e32 v20, 16, v11
	v_and_b32_e32 v21, 0xffff0000, v11
	v_pk_fma_f32 v[18:19], v[30:31], v[32:33], v[18:19] op_sel_hi:[1,0,1] neg_lo:[0,0,1] neg_hi:[0,0,1]
	v_pk_fma_f32 v[12:13], v[12:13], v[32:33], v[20:21] op_sel_hi:[1,0,1] neg_lo:[0,0,1] neg_hi:[0,0,1]
	v_cvt_pk_bf16_f32 v18, v18, v19
	v_cvt_pk_bf16_f32 v19, v12, v13
	ds_write_b128 v113, v[8:11]
	ds_write_b128 v114, v[16:19]
	ds_read_b128 v[8:11], v255 offset:256
	ds_read_b128 v[16:19], v255 offset:272
	s_waitcnt lgkmcnt(0)
	v_pk_mul_f32 v[8:9], v[26:27], v[8:9] op_sel_hi:[0,1]
	s_waitcnt lgkmcnt(0)
	v_pk_mul_f32 v[12:13], v[26:27], v[18:19] op_sel_hi:[0,1]
	v_pk_mul_f32 v[32:33], v[26:27], v[16:17] op_sel_hi:[0,1]
	v_lshl_add_u64 v[16:17], v[14:15], 0, s[42:43]
	ds_read_b128 v[18:21], v255 offset:1024
	ds_read_b128 v[28:31], v255 offset:1040
	s_mov_b64 s[42:43], 0x3800
	v_lshl_add_u64 v[16:17], v[14:15], 0, s[42:43]
	s_mov_b64 s[42:43], 0x5000
	v_lshl_add_u64 v[196:197], v[14:15], 0, s[42:43]
	v_pk_fma_f32 v[8:9], v[8:9], v[208:209], 0 op_sel_hi:[1,1,0]
	v_lshlrev_b32_e32 v208, 16, v62
	v_and_b32_e32 v209, 0xffff0000, v62
	v_pk_mul_f32 v[10:11], v[26:27], v[10:11] op_sel_hi:[0,1]
	s_mov_b64 s[42:43], 0x1000
	s_waitcnt lgkmcnt(0)
	v_pk_mul_f32 v[18:19], v[24:25], v[18:19] op_sel_hi:[0,1]
	s_waitcnt lgkmcnt(0)
	v_pk_mul_f32 v[200:201], v[24:25], v[30:31] op_sel_hi:[0,1]
	v_pk_mul_f32 v[204:205], v[24:25], v[28:29] op_sel_hi:[0,1]
	ds_read_b128 v[28:31], v255 offset:1792
	ds_read_b128 v[94:97], v255 offset:1808
	v_add_co_u32_e32 v16, vcc, s19, v14
	v_pk_fma_f32 v[8:9], v[18:19], v[208:209], v[8:9]
	s_nop 0
	v_addc_co_u32_e32 v17, vcc, 0, v15, vcc
	v_lshlrev_b32_e32 v18, 16, v50
	v_and_b32_e32 v19, 0xffff0000, v50
	v_pk_mul_f32 v[20:21], v[24:25], v[20:21] op_sel_hi:[0,1]
	s_andn2_b64 vcc, exec, s[20:21]
	s_waitcnt lgkmcnt(0)
	v_pk_mul_f32 v[28:29], v[22:23], v[28:29] op_sel_hi:[0,1]
	s_waitcnt lgkmcnt(0)
	v_pk_mul_f32 v[6:7], v[22:23], v[96:97] op_sel_hi:[0,1]
	v_pk_mul_f32 v[206:207], v[22:23], v[94:95] op_sel_hi:[0,1]
	ds_read_b128 v[94:97], v255 offset:2560
	s_nop 0
	ds_read_b128 v[196:199], v255 offset:2576
	v_pk_fma_f32 v[8:9], v[28:29], v[18:19], v[8:9]
	v_lshlrev_b32_e32 v18, 16, v66
	v_and_b32_e32 v19, 0xffff0000, v66
	v_pk_mul_f32 v[30:31], v[22:23], v[30:31] op_sel_hi:[0,1]
	s_waitcnt lgkmcnt(0)
	v_pk_fma_f32 v[8:9], v[94:95], v[18:19], v[8:9]
	s_nop 0
	v_mul_f32_e32 v18, 0xbfb8aa3b, v8
	v_mul_f32_e32 v19, 0xbfb8aa3b, v9
	v_exp_f32_e32 v18, v18
	v_exp_f32_e32 v19, v19
	v_add_f32_e32 v18, 1.0, v18
	v_add_f32_e32 v19, 1.0, v19
	v_rcp_f32_e32 v18, v18
	v_rcp_f32_e32 v19, v19
	s_nop 0
	v_pk_mul_f32 v[18:19], v[8:9], v[18:19]
	v_lshlrev_b32_e32 v8, 16, v55
	v_and_b32_e32 v9, 0xffff0000, v55
	v_pk_fma_f32 v[8:9], v[10:11], v[8:9], 0 op_sel_hi:[1,1,0]
	v_lshlrev_b32_e32 v10, 16, v63
	v_and_b32_e32 v11, 0xffff0000, v63
	v_pk_fma_f32 v[8:9], v[20:21], v[10:11], v[8:9]
	v_lshlrev_b32_e32 v10, 16, v51
	v_and_b32_e32 v11, 0xffff0000, v51
	v_pk_fma_f32 v[8:9], v[30:31], v[10:11], v[8:9]
	v_lshlrev_b32_e32 v10, 16, v67
	v_and_b32_e32 v11, 0xffff0000, v67
	v_pk_fma_f32 v[8:9], v[96:97], v[10:11], v[8:9]
	s_nop 0
	v_mul_f32_e32 v10, 0xbfb8aa3b, v8
	v_mul_f32_e32 v11, 0xbfb8aa3b, v9
	v_exp_f32_e32 v10, v10
	v_exp_f32_e32 v11, v11
	v_add_f32_e32 v10, 1.0, v10
	v_add_f32_e32 v11, 1.0, v11
	v_rcp_f32_e32 v10, v10
	v_rcp_f32_e32 v11, v11
	s_nop 0
	v_pk_mul_f32 v[20:21], v[8:9], v[10:11]
	v_lshlrev_b32_e32 v8, 16, v56
	v_and_b32_e32 v9, 0xffff0000, v56
	v_pk_fma_f32 v[8:9], v[32:33], v[8:9], 0 op_sel_hi:[1,1,0]
	v_lshlrev_b32_e32 v10, 16, v64
	v_and_b32_e32 v11, 0xffff0000, v64
	v_pk_fma_f32 v[8:9], v[204:205], v[10:11], v[8:9]
	v_lshlrev_b32_e32 v10, 16, v52
	v_and_b32_e32 v11, 0xffff0000, v52
	v_pk_fma_f32 v[8:9], v[206:207], v[10:11], v[8:9]
	v_lshlrev_b32_e32 v10, 16, v68
	v_and_b32_e32 v11, 0xffff0000, v68
	s_waitcnt lgkmcnt(0)
; #define LAS __attribute__((address_space(3)))
; DI float bflo(unsigned w) { return __uint_as_float(w << 16); }
; DI float bfhi(unsigned w) { return __uint_as_float(w & 0xffff0000u); }
;     ...
;     for (int which = 0; which < 3; ++which) {
;         const int t = tid >> 3, cg8 = tid & 7; const int col = which * 512 + h * 64 + cg8 * 8;
;         float acc[8];
; #pragma unroll
;         for (int e = 0; e < 8; ++e) acc[e] = 0.f;
; #pragma unroll
;         for (int j = 0; j < 4; ++j) { const int sp = n * 64 + t - 3 + j; const float ok = sp >= 0 ? 1.f : 0.f;
;             const u32x4 xv = xin[which * 4 + j];
;             const f32x4 w0 = *(const f32x4*)(conv_w + j * 1536 + col) * ok, w1 = *(const f32x4*)(conv_w + j * 1536 + col + 4) * ok;
;             acc[0] += w0[0] * bflo(xv.x); acc[1] += w0[1] * bfhi(xv.x); acc[2] += w0[2] * bflo(xv.y); acc[3] += w0[3] * bfhi(xv.y);
;             acc[4] += w1[0] * bflo(xv.z); acc[5] += w1[1] * bfhi(xv.z); acc[6] += w1[2] * bflo(xv.w); acc[7] += w1[3] * bfhi(xv.w); }
; #pragma unroll
;         for (int e = 0; e < 8; ++e) acc[e] = silu_f(acc[e]);
;         if (which == 2) { LAS float* dst = vc + t * 68 + cg8 * 8; *(LAS f32x4*)dst = (f32x4){acc[0], acc[1], acc[2], acc[3]}; *(LAS f32x4*)(dst + 4) = (f32x4){acc[4], acc[5], acc[6], acc[7]}; }
;         else {
;             float ss = (acc[0] * acc[0] + acc[1] * acc[1]) + (acc[2] * acc[2] + acc[3] * acc[3]) + (acc[4] * acc[4] + acc[5] * acc[5]) + (acc[6] * acc[6] + acc[7] * acc[7]);
;             ss += __shfl_xor(ss, 1); ss += __shfl_xor(ss, 2); ss += __shfl_xor(ss, 4);
;             const float sc = (which ? 1.0f : 0.125f) * __builtin_amdgcn_rsqf(ss + 1e-6f);
;             const f32x4 y0 = (f32x4){acc[0], acc[1], acc[2], acc[3]} * sc, y1 = (f32x4){acc[4], acc[5], acc[6], acc[7]} * sc;
;             LAS float* dst = (which ? kc : qc) + t * 68 + cg8 * 8; *(LAS f32x4*)dst = y0; *(LAS f32x4*)(dst + 4) = y1;
;             u32x4 hh; hh.x = pk2(y0[0], y0[1]); hh.y = pk2(y0[2], y0[3]); hh.z = pk2(y1[0], y1[1]); hh.w = pk2(y1[2], y1[3]);
;             u32x4 lo; lo.x = pk2(y0[0] - bflo(hh.x), y0[1] - bfhi(hh.x)); lo.y = pk2(y0[2] - bflo(hh.y), y0[3] - bfhi(hh.y)); lo.z = pk2(y1[0] - bflo(hh.z), y1[1] - bfhi(hh.z)); lo.w = pk2(y1[2] - bflo(hh.w), y1[3] - bfhi(hh.w));
;             *(LAS u32x4*)((which ? KH : QH) + t * 72 + cg8 * 8) = hh; *(LAS u32x4*)((which ? KL : QL) + t * 72 + cg8 * 8) = lo; }
	v_pk_fma_f32 v[8:9], v[196:197], v[10:11], v[8:9]
	s_nop 0
	v_mul_f32_e32 v10, 0xbfb8aa3b, v8
	v_mul_f32_e32 v11, 0xbfb8aa3b, v9
	v_exp_f32_e32 v10, v10
	v_exp_f32_e32 v11, v11
	v_add_f32_e32 v10, 1.0, v10
	v_add_f32_e32 v11, 1.0, v11
	v_rcp_f32_e32 v10, v10
	v_rcp_f32_e32 v11, v11
	s_nop 0
	v_pk_mul_f32 v[28:29], v[8:9], v[10:11]
	v_lshlrev_b32_e32 v8, 16, v57
	v_and_b32_e32 v9, 0xffff0000, v57
	v_pk_fma_f32 v[8:9], v[12:13], v[8:9], 0 op_sel_hi:[1,1,0]
	v_lshlrev_b32_e32 v10, 16, v65
	v_and_b32_e32 v11, 0xffff0000, v65
	v_pk_fma_f32 v[8:9], v[200:201], v[10:11], v[8:9]
	v_lshlrev_b32_e32 v10, 16, v53
	v_and_b32_e32 v11, 0xffff0000, v53
	v_pk_fma_f32 v[6:7], v[6:7], v[10:11], v[8:9]
	v_lshlrev_b32_e32 v8, 16, v69
	v_and_b32_e32 v9, 0xffff0000, v69
	v_pk_fma_f32 v[6:7], v[198:199], v[8:9], v[6:7]
	v_mov_b32_e32 v11, v29
	v_mul_f32_e32 v8, 0xbfb8aa3b, v7
	v_exp_f32_e32 v8, v8
	s_nop 0
	v_add_f32_e32 v8, 1.0, v8
	v_rcp_f32_e32 v9, v8
	v_mul_f32_e32 v8, 0xbfb8aa3b, v6
	v_exp_f32_e32 v8, v8
	s_nop 0
	v_add_f32_e32 v8, 1.0, v8
	v_rcp_f32_e32 v8, v8
	s_nop 0
	v_pk_mul_f32 v[30:31], v[6:7], v[8:9]
	v_mov_b32_e32 v8, v19
	v_mov_b32_e32 v9, v21
	v_mov_b32_e32 v6, v18
	v_mov_b32_e32 v7, v20
	v_pk_mul_f32 v[8:9], v[8:9], v[8:9]
	v_mov_b32_e32 v10, v31
	v_pk_fma_f32 v[6:7], v[6:7], v[6:7], v[8:9]
	v_mov_b32_e32 v8, v30
	v_mov_b32_e32 v9, v28
	v_pk_mul_f32 v[10:11], v[10:11], v[10:11]
	v_add_f32_e32 v6, v6, v7
	v_pk_fma_f32 v[8:9], v[8:9], v[8:9], v[10:11]
	s_nop 0
	v_add_f32_e32 v6, v9, v6
	v_add_f32_e32 v6, v8, v6
	ds_bpermute_b32 v7, v101, v6
	s_waitcnt lgkmcnt(0)
	v_add_f32_e32 v6, v6, v7
	ds_bpermute_b32 v7, v102, v6
	s_waitcnt lgkmcnt(0)
	v_add_f32_e32 v6, v6, v7
	ds_bpermute_b32 v7, v103, v6
	s_waitcnt lgkmcnt(0)
	v_add_f32_e32 v6, v6, v7
	v_add_f32_e32 v6, 0x358637bd, v6
	v_rsq_f32_e32 v32, v6
	s_nop 0
	v_pk_mul_f32 v[8:9], v[20:21], v[32:33] op_sel_hi:[1,0]
	v_pk_mul_f32 v[6:7], v[18:19], v[32:33] op_sel_hi:[1,0]
	v_pk_mul_f32 v[12:13], v[30:31], v[32:33] op_sel_hi:[1,0]
	v_pk_mul_f32 v[10:11], v[28:29], v[32:33] op_sel_hi:[1,0]
	ds_write_b128 v112, v[6:9] offset:17408
	ds_write_b128 v112, v[10:13] offset:17424
	v_cvt_pk_bf16_f32 v6, v6, v7
	v_cvt_pk_bf16_f32 v7, v8, v9
	v_cvt_pk_bf16_f32 v8, v10, v11
	v_cvt_pk_bf16_f32 v9, v12, v13
	v_lshlrev_b32_e32 v10, 16, v6
	v_and_b32_e32 v11, 0xffff0000, v6
	v_lshlrev_b32_e32 v12, 16, v7
	v_and_b32_e32 v13, 0xffff0000, v7
	v_pk_fma_f32 v[10:11], v[18:19], v[32:33], v[10:11] op_sel_hi:[1,0,1] neg_lo:[0,0,1] neg_hi:[0,0,1]
	v_pk_fma_f32 v[12:13], v[20:21], v[32:33], v[12:13] op_sel_hi:[1,0,1] neg_lo:[0,0,1] neg_hi:[0,0,1]
	v_cvt_pk_bf16_f32 v10, v10, v11
	v_cvt_pk_bf16_f32 v11, v12, v13
	v_lshlrev_b32_e32 v12, 16, v8
	v_and_b32_e32 v13, 0xffff0000, v8
	v_lshlrev_b32_e32 v18, 16, v9
	v_and_b32_e32 v19, 0xffff0000, v9
	v_pk_fma_f32 v[12:13], v[28:29], v[32:33], v[12:13] op_sel_hi:[1,0,1] neg_lo:[0,0,1] neg_hi:[0,0,1]
	v_pk_fma_f32 v[18:19], v[30:31], v[32:33], v[18:19] op_sel_hi:[1,0,1] neg_lo:[0,0,1] neg_hi:[0,0,1]
	v_cvt_pk_bf16_f32 v12, v12, v13
	v_cvt_pk_bf16_f32 v13, v18, v19
	ds_write_b128 v115, v[6:9]
	ds_write_b128 v116, v[10:13]
	v_lshl_add_u64 v[10:11], v[14:15], 0, s[42:43]
	ds_read_b128 v[6:9], v255 offset:512
	s_nop 0
	ds_read_b128 v[10:13], v255 offset:528
	s_mov_b64 s[42:43], 0x2800
	v_lshl_add_u64 v[2:3], v[14:15], 0, s[42:43]
	s_mov_b64 s[42:43], 0x5800
	s_waitcnt lgkmcnt(0)
	v_pk_mul_f32 v[6:7], v[26:27], v[6:7] op_sel_hi:[0,1]
	s_waitcnt lgkmcnt(0)
	v_pk_mul_f32 v[28:29], v[26:27], v[12:13] op_sel_hi:[0,1]
	v_pk_mul_f32 v[94:95], v[26:27], v[10:11] op_sel_hi:[0,1]
	ds_read_b128 v[10:13], v255 offset:1280
	ds_read_b128 v[18:21], v255 offset:1296
	v_pk_mul_f32 v[8:9], v[26:27], v[8:9] op_sel_hi:[0,1]
	s_waitcnt lgkmcnt(0)
	v_pk_mul_f32 v[10:11], v[24:25], v[10:11] op_sel_hi:[0,1]
	s_waitcnt lgkmcnt(0)
	v_pk_mul_f32 v[96:97], v[24:25], v[18:19] op_sel_hi:[0,1]
	v_lshl_add_u64 v[18:19], v[14:15], 0, s[28:29]
	v_pk_mul_f32 v[30:31], v[24:25], v[20:21] op_sel_hi:[0,1]
	ds_read_b128 v[2:5], v255 offset:2048
	s_nop 0
	ds_read_b128 v[18:21], v255 offset:2064
	v_pk_mul_f32 v[12:13], v[24:25], v[12:13] op_sel_hi:[0,1]
	s_waitcnt lgkmcnt(0)
	v_pk_mul_f32 v[4:5], v[22:23], v[4:5] op_sel_hi:[0,1]
	s_waitcnt lgkmcnt(0)
	v_pk_mul_f32 v[98:99], v[22:23], v[18:19] op_sel_hi:[0,1]
	v_lshl_add_u64 v[18:19], v[14:15], 0, s[42:43]
	v_pk_mul_f32 v[32:33], v[22:23], v[20:21] op_sel_hi:[0,1]
	ds_read_b128 v[14:17], v255 offset:2816
	s_nop 0
	ds_read_b128 v[18:21], v255 offset:2832
	v_pk_mul_f32 v[2:3], v[22:23], v[2:3] op_sel_hi:[0,1]
	v_lshlrev_b32_e32 v22, 16, v34
	v_and_b32_e32 v23, 0xffff0000, v34
	v_pk_fma_f32 v[6:7], v[6:7], v[22:23], 0 op_sel_hi:[1,1,0]
	v_lshlrev_b32_e32 v22, 16, v38
	v_and_b32_e32 v23, 0xffff0000, v38
	v_pk_fma_f32 v[6:7], v[10:11], v[22:23], v[6:7]
	v_lshlrev_b32_e32 v10, 16, v42
	v_and_b32_e32 v11, 0xffff0000, v42
	v_pk_fma_f32 v[2:3], v[2:3], v[10:11], v[6:7]
	v_lshlrev_b32_e32 v10, 16, v35
	v_and_b32_e32 v11, 0xffff0000, v35
	v_pk_fma_f32 v[8:9], v[8:9], v[10:11], 0 op_sel_hi:[1,1,0]
	v_lshlrev_b32_e32 v10, 16, v39
	v_and_b32_e32 v11, 0xffff0000, v39
	v_lshlrev_b32_e32 v6, 16, v46
	v_and_b32_e32 v7, 0xffff0000, v46
	v_pk_fma_f32 v[8:9], v[12:13], v[10:11], v[8:9]
	v_lshlrev_b32_e32 v10, 16, v43
	v_and_b32_e32 v11, 0xffff0000, v43
	v_pk_fma_f32 v[4:5], v[4:5], v[10:11], v[8:9]
	v_lshlrev_b32_e32 v8, 16, v47
	v_and_b32_e32 v9, 0xffff0000, v47
	v_lshlrev_b32_e32 v10, 16, v37
	v_and_b32_e32 v11, 0xffff0000, v37
	v_pk_fma_f32 v[10:11], v[28:29], v[10:11], 0 op_sel_hi:[1,1,0]
	v_lshlrev_b32_e32 v12, 16, v41
	v_and_b32_e32 v13, 0xffff0000, v41
	v_pk_fma_f32 v[10:11], v[30:31], v[12:13], v[10:11]
	v_lshlrev_b32_e32 v12, 16, v45
	v_and_b32_e32 v13, 0xffff0000, v45
	v_pk_fma_f32 v[10:11], v[32:33], v[12:13], v[10:11]
	v_lshlrev_b32_e32 v12, 16, v49
	v_and_b32_e32 v13, 0xffff0000, v49
	s_waitcnt lgkmcnt(0)
; #define LAS __attribute__((address_space(3)))
; DI float bflo(unsigned w) { return __uint_as_float(w << 16); }
; DI float bfhi(unsigned w) { return __uint_as_float(w & 0xffff0000u); }
; DI float silu_f(float g) { return g * frcp(1.f + fexp2(-1.4426950408889634f * g)); }
;     ...
;         for (int j = 0; j < 4; ++j) { const int sp = n * 64 + t - 3 + j; const float ok = sp >= 0 ? 1.f : 0.f;
;             const u32x4 xv = xin[which * 4 + j];
;             const f32x4 w0 = *(const f32x4*)(conv_w + j * 1536 + col) * ok, w1 = *(const f32x4*)(conv_w + j * 1536 + col + 4) * ok;
;             acc[0] += w0[0] * bflo(xv.x); acc[1] += w0[1] * bfhi(xv.x); acc[2] += w0[2] * bflo(xv.y); acc[3] += w0[3] * bfhi(xv.y);
;             acc[4] += w1[0] * bflo(xv.z); acc[5] += w1[1] * bfhi(xv.z); acc[6] += w1[2] * bflo(xv.w); acc[7] += w1[3] * bfhi(xv.w); }
; #pragma unroll
;         for (int e = 0; e < 8; ++e) acc[e] = silu_f(acc[e]);
;         if (which == 2) { LAS float* dst = vc + t * 68 + cg8 * 8; *(LAS f32x4*)dst = (f32x4){acc[0], acc[1], acc[2], acc[3]}; *(LAS f32x4*)(dst + 4) = (f32x4){acc[4], acc[5], acc[6], acc[7]}; }
	v_pk_fma_f32 v[2:3], v[14:15], v[6:7], v[2:3]
	s_nop 0
	v_mul_f32_e32 v6, 0xbfb8aa3b, v2
	v_mul_f32_e32 v7, 0xbfb8aa3b, v3
	v_pk_fma_f32 v[4:5], v[16:17], v[8:9], v[4:5]
	v_exp_f32_e32 v6, v6
	v_exp_f32_e32 v7, v7
	v_mul_f32_e32 v8, 0xbfb8aa3b, v4
	v_mul_f32_e32 v9, 0xbfb8aa3b, v5
	v_exp_f32_e32 v8, v8
	v_exp_f32_e32 v9, v9
	v_add_f32_e32 v6, 1.0, v6
	v_add_f32_e32 v7, 1.0, v7
	v_rcp_f32_e32 v6, v6
	v_rcp_f32_e32 v7, v7
	v_add_f32_e32 v8, 1.0, v8
	v_add_f32_e32 v9, 1.0, v9
	v_rcp_f32_e32 v8, v8
	v_rcp_f32_e32 v9, v9
	s_waitcnt lgkmcnt(0)
	v_pk_fma_f32 v[10:11], v[20:21], v[12:13], v[10:11]
	v_pk_mul_f32 v[2:3], v[2:3], v[6:7]
	v_mul_f32_e32 v12, 0xbfb8aa3b, v11
	v_lshlrev_b32_e32 v6, 16, v36
	v_and_b32_e32 v7, 0xffff0000, v36
	v_exp_f32_e32 v12, v12
	v_pk_mul_f32 v[4:5], v[4:5], v[8:9]
	v_pk_fma_f32 v[6:7], v[94:95], v[6:7], 0 op_sel_hi:[1,1,0]
	v_lshlrev_b32_e32 v8, 16, v40
	v_and_b32_e32 v9, 0xffff0000, v40
	v_pk_fma_f32 v[6:7], v[96:97], v[8:9], v[6:7]
	v_lshlrev_b32_e32 v8, 16, v44
	v_and_b32_e32 v9, 0xffff0000, v44
	v_pk_fma_f32 v[6:7], v[98:99], v[8:9], v[6:7]
	v_lshlrev_b32_e32 v8, 16, v48
	v_and_b32_e32 v9, 0xffff0000, v48
	v_pk_fma_f32 v[6:7], v[18:19], v[8:9], v[6:7]
	v_add_f32_e32 v12, 1.0, v12
	v_mul_f32_e32 v8, 0xbfb8aa3b, v6
	v_mul_f32_e32 v9, 0xbfb8aa3b, v7
	v_rcp_f32_e32 v13, v12
	v_mul_f32_e32 v12, 0xbfb8aa3b, v10
	v_exp_f32_e32 v8, v8
	v_exp_f32_e32 v9, v9
	v_exp_f32_e32 v12, v12
	v_add_f32_e32 v8, 1.0, v8
	v_add_f32_e32 v9, 1.0, v9
	v_add_f32_e32 v12, 1.0, v12
	v_rcp_f32_e32 v8, v8
	v_rcp_f32_e32 v9, v9
	v_rcp_f32_e32 v12, v12
	v_pk_mul_f32 v[6:7], v[6:7], v[8:9]
	v_pk_mul_f32 v[8:9], v[10:11], v[12:13]
	ds_write_b128 v176, v[2:5] offset:34816
	ds_write_b128 v176, v[6:9] offset:34832
	s_cbranch_vccnz .LBB0_436
; DI float bf2f(bf16_t u) { return __uint_as_float(((unsigned)u) << 16); }
;     ...
;     { const float ga = bf2f(gain), gb = bf2f(gbin);
;         const float x = ga + dt_bias[h]; const float sp = fmaxf(x, 0.f) + log1pf(expf(-fabsf(x)));
;         float gv = -expf(a_log[h]) * sp; const float bv = 1.f / (1.f + expf(-gb));
;         if (wid == 0) {
; #pragma unroll
;             for (int o = 1; o < 64; o <<= 1) { const float tt = __shfl_up(gv, o); if (lane >= o) gv += tt; }
;             gcs[lane] = gv; bet[lane] = bv; } }
	s_lshl_b32 s3, s3, 2
	v_mov_b32_e32 v2, s3
	v_readlane_b32 s52, v247, 9
	s_waitcnt vmcnt(0)
	v_mov_b32_e32 v3, v252
	v_readlane_b32 s53, v247, 10
	v_lshlrev_b32_e32 v5, 16, v1
	s_mov_b32 s3, 0xb2a5705f
	v_readlane_b32 s54, v247, 11
	v_readlane_b32 s55, v247, 12
	v_readlane_b32 s56, v247, 13
	v_mov_b32_e32 v4, v253
	v_lshlrev_b32_e32 v2, 16, v100
	v_mul_f32_e32 v6, 0xbfb8aa3b, v2
	v_rndne_f32_e32 v7, v6
	v_fma_f32 v8, v2, s78, -v6
	v_sub_f32_e32 v6, v6, v7
	v_fmac_f32_e32 v8, 0xb2a5705f, v2
	v_add_f32_e32 v6, v6, v8
	v_cvt_i32_f32_e32 v7, v7
	v_exp_f32_e32 v6, v6
	v_readlane_b32 s57, v247, 14
	v_readlane_b32 s58, v247, 15
	v_readlane_b32 s59, v247, 16
	v_ldexp_f32 v6, v6, v7
	v_readlane_b32 s60, v247, 17
	v_readlane_b32 s61, v247, 18
	v_readlane_b32 s62, v247, 19
	v_readlane_b32 s63, v247, 20
	v_readlane_b32 s64, v247, 21
	v_readlane_b32 s65, v247, 22
	v_readlane_b32 s66, v247, 23
	v_readlane_b32 s67, v247, 24
	s_waitcnt vmcnt(1)
	v_mul_f32_e32 v8, 0x3fb8aa3b, v3
	v_rndne_f32_e32 v9, v8
	v_cmp_ngt_f32_e32 vcc, s95, v3
	s_waitcnt vmcnt(0)
	v_add_f32_e32 v4, v4, v5
	v_fma_f32 v5, v3, s27, -v8
	v_mul_f32_e64 v10, |v4|, s78
	v_fmac_f32_e32 v5, 0x32a5705f, v3
	v_sub_f32_e32 v8, v8, v9
	v_fma_f32 v12, |v4|, s78, -v10
	v_rndne_f32_e32 v13, v10
	v_add_f32_e32 v5, v8, v5
	v_cvt_i32_f32_e32 v9, v9
	v_fma_f32 v8, |v4|, s3, v12
	v_sub_f32_e32 v10, v10, v13
	v_exp_f32_e32 v5, v5
	v_add_f32_e32 v8, v10, v8
	v_cvt_i32_f32_e32 v12, v13
	v_exp_f32_e32 v8, v8
	v_ldexp_f32 v5, v5, v9
	v_cndmask_b32_e32 v5, 0, v5, vcc
	v_cmp_nlt_f32_e32 vcc, s16, v3
	v_ldexp_f32 v8, v8, v12
	v_max_f32_e32 v11, 0, v4
	v_cndmask_b32_e32 v3, v193, v5, vcc
	v_cmp_ngt_f32_e64 vcc, |v4|, s79
	s_mov_b32 s3, 0x3f2aaaab
	s_nop 0
	v_cndmask_b32_e32 v5, 0, v8, vcc
	v_cmp_nlt_f32_e64 vcc, |v4|, s26
	s_nop 1
	v_cndmask_b32_e32 v8, v193, v5, vcc
	v_add_f32_e32 v9, 1.0, v8
	v_cvt_f64_f32_e32 v[4:5], v9
	v_frexp_mant_f32_e32 v10, v9
	v_add_f32_e32 v12, -1.0, v9
	v_frexp_exp_i32_f64_e32 v4, v[4:5]
	v_cmp_gt_f32_e32 vcc, s3, v10
	v_sub_f32_e32 v5, v8, v12
	v_sub_f32_e32 v12, v12, v9
	v_subbrev_co_u32_e32 v4, vcc, 0, v4, vcc
	v_add_f32_e32 v10, 1.0, v12
	v_cvt_f32_i32_e32 v12, v4
	v_sub_u32_e32 v4, 0, v4
	v_add_f32_e32 v5, v5, v10
	v_ldexp_f32 v9, v9, v4
	v_ldexp_f32 v4, v5, v4
	v_add_f32_e32 v5, -1.0, v9
	v_add_f32_e32 v10, 1.0, v9
	v_add_f32_e32 v13, 1.0, v5
	v_add_f32_e32 v14, -1.0, v10
	v_mul_f32_e32 v15, 0x3f317218, v12
	v_sub_f32_e32 v13, v9, v13
	v_sub_f32_e32 v9, v9, v14
	s_mov_b32 s3, 0x3f317218
	v_fma_f32 v14, v12, s3, -v15
	v_add_f32_e32 v13, v4, v13
	v_add_f32_e32 v4, v4, v9
	v_fmac_f32_e32 v14, 0xb102e308, v12
	v_add_f32_e32 v12, v10, v4
	v_rcp_f32_e32 v17, v12
	v_add_f32_e32 v9, v5, v13
	v_add_f32_e32 v16, v15, v14
	v_sub_f32_e32 v10, v10, v12
	v_sub_f32_e32 v5, v5, v9
	v_add_f32_e32 v4, v4, v10
	v_add_f32_e32 v5, v13, v5
	v_sub_f32_e32 v10, v16, v15
	v_mul_f32_e32 v13, v9, v17
	v_sub_f32_e32 v10, v14, v10
	v_mul_f32_e32 v14, v12, v13
	v_fma_f32 v15, v13, v12, -v14
	v_fmac_f32_e32 v15, v13, v4
	v_add_f32_e32 v18, v14, v15
	v_sub_f32_e32 v19, v9, v18
	v_sub_f32_e32 v9, v9, v19
	v_sub_f32_e32 v14, v18, v14
	v_sub_f32_e32 v9, v9, v18
	v_sub_f32_e32 v14, v14, v15
	v_add_f32_e32 v5, v5, v9
	v_add_f32_e32 v5, v14, v5
	v_add_f32_e32 v9, v19, v5
	v_mul_f32_e32 v14, v17, v9
	v_sub_f32_e32 v15, v19, v9
	v_mul_f32_e32 v19, v12, v14
	v_fma_f32 v12, v14, v12, -v19
	v_add_f32_e32 v18, v13, v14
	v_fmac_f32_e32 v12, v14, v4
	v_sub_f32_e32 v13, v18, v13
	v_add_f32_e32 v4, v19, v12
	v_sub_f32_e32 v13, v14, v13
	v_sub_f32_e32 v14, v9, v4
	v_sub_f32_e32 v9, v9, v14
	v_add_f32_e32 v5, v5, v15
	v_sub_f32_e32 v15, v4, v19
	v_sub_f32_e32 v4, v9, v4
	v_sub_f32_e32 v12, v15, v12
	v_add_f32_e32 v4, v5, v4
	v_add_f32_e32 v4, v12, v4
	v_add_f32_e32 v4, v14, v4
	v_mul_f32_e32 v4, v17, v4
	v_add_f32_e32 v4, v13, v4
	v_add_f32_e32 v5, v18, v4
	v_mul_f32_e32 v12, v5, v5
	v_fmamk_f32 v14, v12, 0x3e9b6dac, v177
	v_ldexp_f32 v9, v5, 1
	v_sub_f32_e32 v13, v5, v18
	v_mul_f32_e32 v5, v5, v12
	v_fmaak_f32 v12, v12, v14, 0x3f2aaada
	v_mul_f32_e32 v5, v5, v12
	v_add_f32_e32 v12, v9, v5
	v_sub_f32_e32 v4, v4, v13
	v_sub_f32_e32 v9, v12, v9
	v_ldexp_f32 v4, v4, 1
	v_sub_f32_e32 v5, v5, v9
	v_add_f32_e32 v4, v4, v5
	v_add_f32_e32 v5, v12, v4
	v_add_f32_e32 v9, v16, v5
	v_sub_f32_e32 v12, v5, v12
	v_sub_f32_e32 v4, v4, v12
	v_sub_f32_e32 v12, v9, v16
	v_sub_f32_e32 v5, v5, v12
	v_sub_f32_e32 v12, v9, v12
	v_add_f32_e32 v13, v10, v4
	v_sub_f32_e32 v12, v16, v12
	v_sub_f32_e32 v14, v13, v10
	v_add_f32_e32 v5, v5, v12
	v_sub_f32_e32 v12, v13, v14
	v_add_f32_e32 v5, v13, v5
	v_sub_f32_e32 v10, v10, v12
	v_add_f32_e32 v12, v9, v5
	v_sub_f32_e32 v4, v4, v14
	v_sub_f32_e32 v9, v12, v9
	v_add_f32_e32 v4, v4, v10
	v_sub_f32_e32 v5, v5, v9
	v_add_f32_e32 v4, v4, v5
	s_mov_b32 s3, 0x7f800000
	v_add_f32_e32 v4, v12, v4
	v_cmp_neq_f32_e32 vcc, s3, v8
	s_mov_b32 s3, 0x33800000
	s_nop 0
	v_cndmask_b32_e32 v4, v193, v4, vcc
	v_cmp_lt_f32_e64 vcc, |v8|, s3
	s_nop 1
	v_cndmask_b32_e32 v4, v4, v8, vcc
	v_add_f32_e32 v4, v11, v4
	v_mul_f32_e64 v5, v4, -v3
	ds_bpermute_b32 v8, v104, v5
	v_cmp_nlt_f32_e32 vcc, s79, v2
	s_waitcnt lgkmcnt(0)
	v_fma_f32 v3, v4, -v3, v8
	v_cndmask_b32_e64 v3, v3, v5, s[4:5]
	ds_bpermute_b32 v4, v105, v3
	v_cndmask_b32_e32 v5, 0, v6, vcc
	v_cmp_ngt_f32_e32 vcc, s26, v2
	s_waitcnt lgkmcnt(0)
	v_add_f32_e32 v4, v3, v4
	v_cndmask_b32_e64 v3, v4, v3, s[6:7]
	ds_bpermute_b32 v4, v106, v3
	v_cndmask_b32_e32 v2, v193, v5, vcc
	v_add_f32_e32 v2, 1.0, v2
	v_div_scale_f32 v5, s[42:43], v2, v2, 1.0
	s_waitcnt lgkmcnt(0)
	v_add_f32_e32 v4, v3, v4
	v_cndmask_b32_e64 v3, v4, v3, s[8:9]
	ds_bpermute_b32 v4, v107, v3
	v_rcp_f32_e32 v6, v5
	v_div_scale_f32 v7, vcc, 1.0, v2, 1.0
	s_waitcnt lgkmcnt(0)
	v_add_f32_e32 v4, v3, v4
	v_cndmask_b32_e64 v3, v4, v3, s[10:11]
	ds_bpermute_b32 v4, v108, v3
	v_fma_f32 v8, -v5, v6, 1.0
	v_fmac_f32_e32 v6, v8, v6
	v_mul_f32_e32 v8, v7, v6
	v_fma_f32 v9, -v5, v8, v7
	s_waitcnt lgkmcnt(0)
	v_add_f32_e32 v4, v3, v4
	v_cndmask_b32_e64 v3, v4, v3, s[12:13]
	ds_bpermute_b32 v4, v109, v3
	v_fmac_f32_e32 v8, v9, v6
	v_fma_f32 v5, -v5, v8, v7
	v_div_fmas_f32 v5, v5, v6, v8
	v_div_fixup_f32 v2, v5, v2, 1.0
	s_waitcnt lgkmcnt(0)
	v_add_f32_e32 v4, v3, v4
	v_cndmask_b32_e64 v3, v4, v3, s[14:15]
	ds_write_b32 v117, v3
	ds_write_b32 v118, v2

; #define LAS __attribute__((address_space(3)))
; DI float bflo(unsigned w) { return __uint_as_float(w << 16); }
; DI float bfhi(unsigned w) { return __uint_as_float(w & 0xffff0000u); }
; DI float bf2f(bf16_t u) { return __uint_as_float(((unsigned)u) << 16); }
; DI float silu_f(float g) { return g * frcp(1.f + fexp2(-1.4426950408889634f * g)); }
;     ...
;     for (int which = 0; which < 3; ++which) {
;         const int t = tid >> 3, cg8 = tid & 7; const int col = which * 512 + h * 64 + cg8 * 8;
;         float acc[8];
; #pragma unroll
;         for (int e = 0; e < 8; ++e) acc[e] = 0.f;
; #pragma unroll
;         for (int j = 0; j < 4; ++j) { const int sp = n * 64 + t - 3 + j; const float ok = sp >= 0 ? 1.f : 0.f;
;             const u32x4 xv = xin[which * 4 + j];
;             const f32x4 w0 = *(const f32x4*)(conv_w + j * 1536 + col) * ok, w1 = *(const f32x4*)(conv_w + j * 1536 + col + 4) * ok;
;             acc[0] += w0[0] * bflo(xv.x); acc[1] += w0[1] * bfhi(xv.x); acc[2] += w0[2] * bflo(xv.y); acc[3] += w0[3] * bfhi(xv.y);
;             acc[4] += w1[0] * bflo(xv.z); acc[5] += w1[1] * bfhi(xv.z); acc[6] += w1[2] * bflo(xv.w); acc[7] += w1[3] * bfhi(xv.w); }
; #pragma unroll
;         for (int e = 0; e < 8; ++e) acc[e] = silu_f(acc[e]);
;         if (which == 2) { LAS float* dst = vc + t * 68 + cg8 * 8; *(LAS f32x4*)dst = (f32x4){acc[0], acc[1], acc[2], acc[3]}; *(LAS f32x4*)(dst + 4) = (f32x4){acc[4], acc[5], acc[6], acc[7]}; }
;         else {
;             float ss = (acc[0] * acc[0] + acc[1] * acc[1]) + (acc[2] * acc[2] + acc[3] * acc[3]) + (acc[4] * acc[4] + acc[5] * acc[5]) + (acc[6] * acc[6] + acc[7] * acc[7]);
;             ss += __shfl_xor(ss, 1); ss += __shfl_xor(ss, 2); ss += __shfl_xor(ss, 4);
;             const float sc = (which ? 1.0f : 0.125f) * __builtin_amdgcn_rsqf(ss + 1e-6f);
;             const f32x4 y0 = (f32x4){acc[0], acc[1], acc[2], acc[3]} * sc, y1 = (f32x4){acc[4], acc[5], acc[6], acc[7]} * sc;
;             LAS float* dst = (which ? kc : qc) + t * 68 + cg8 * 8; *(LAS f32x4*)dst = y0; *(LAS f32x4*)(dst + 4) = y1;
;     ...
;     { const float ga = bf2f(gain), gb = bf2f(gbin);
;         const float x = ga + dt_bias[h]; const float sp = fmaxf(x, 0.f) + log1pf(expf(-fabsf(x)));
;         float gv = -expf(a_log[h]) * sp; const float bv = 1.f / (1.f + expf(-gb));
.LBB0_1745:
	s_lshl_b32 s16, s68, 6
	s_and_b32 s16, s16, 0xfc0
	v_add_u32_e32 v2, s16, v110
	v_cmp_lt_u32_e32 vcc, 2, v2
	s_bfe_u32 s24, s68, 0x30006
	s_bfe_u32 s100, s70, 0x30006
	s_xor_b32 s100, s100, s24
	s_mul_i32 s100, s100, 0x300
	v_lshlrev_b32_e32 v255, 2, v111
	v_add_u32_e32 v255, s100, v255
	v_add_u32_e32 v255, 0x24100, v255
	s_mov_b64 s[16:17], 0x1800
	v_cndmask_b32_e64 v26, 0, 1.0, vcc
	v_cmp_lt_u32_e32 vcc, 1, v2
	s_waitcnt vmcnt(0)
	s_lshl_b32 s101, s24, 2
	v_mov_b32_e32 v254, s101
	v_readlane_b32 s100, v247, 9
	v_readlane_b32 s101, v247, 10
	global_load_dword v252, v254, s[50:51] offset:32
	s_nop 4
	global_load_dword v253, v254, s[100:101] offset:32
	v_lshlrev_b32_e32 v208, 16, v54
	v_and_b32_e32 v209, 0xffff0000, v54
	v_cndmask_b32_e64 v24, 0, 1.0, vcc
	v_cmp_eq_u32_e32 vcc, 0, v2
	v_lshlrev_b32_e32 v2, 2, v111
	v_lshl_or_b32 v82, s24, 8, v2
	ds_read_b128 v[18:21], v255 offset:0
	ds_read_b128 v[2:5], v255 offset:16
	v_lshl_add_u64 v[14:15], s[44:45], 0, v[82:83]
	v_cndmask_b32_e64 v22, 1.0, 0, vcc
	s_waitcnt lgkmcnt(0)
	v_pk_mul_f32 v[18:19], v[26:27], v[18:19] op_sel_hi:[0,1]
	v_pk_mul_f32 v[8:9], v[4:5], v[26:27] op_sel_hi:[1,0]
	v_lshl_add_u64 v[4:5], v[14:15], 0, s[16:17]
	s_movk_i32 s16, 0x1000
	v_pk_mul_f32 v[10:11], v[2:3], v[26:27] op_sel_hi:[1,0]
	v_add_co_u32_e32 v2, vcc, s16, v14
	s_mov_b64 s[16:17], 0x3000
	s_nop 0
	v_addc_co_u32_e32 v3, vcc, 0, v15, vcc
	ds_read_b128 v[28:31], v255 offset:768
	s_nop 0
	ds_read_b128 v[4:7], v255 offset:784
	v_lshl_add_u64 v[32:33], v[14:15], 0, s[16:17]
	s_movk_i32 s16, 0x3000
	v_pk_mul_f32 v[20:21], v[26:27], v[20:21] op_sel_hi:[0,1]
	s_waitcnt lgkmcnt(0)
	v_pk_mul_f32 v[28:29], v[24:25], v[28:29] op_sel_hi:[0,1]
	v_pk_mul_f32 v[12:13], v[6:7], v[24:25] op_sel_hi:[1,0]
	v_add_co_u32_e32 v6, vcc, s16, v14
	s_movk_i32 s16, 0x4000
	s_nop 0
	v_addc_co_u32_e32 v7, vcc, 0, v15, vcc
	v_pk_mul_f32 v[16:17], v[4:5], v[24:25] op_sel_hi:[1,0]
	v_add_co_u32_e32 v4, vcc, s16, v14
	s_mov_b64 s[16:17], 0x4800
	s_nop 0
	v_addc_co_u32_e32 v5, vcc, 0, v15, vcc
	ds_read_b128 v[94:97], v255 offset:1536
	ds_read_b128 v[196:199], v255 offset:1552
	v_lshl_add_u64 v[200:201], v[14:15], 0, s[16:17]
	v_pk_mul_f32 v[30:31], v[24:25], v[30:31] op_sel_hi:[0,1]
	s_mov_b64 s[16:17], 0x2000
	s_waitcnt lgkmcnt(0)
	v_pk_mul_f32 v[94:95], v[22:23], v[94:95] op_sel_hi:[0,1]
	v_pk_mul_f32 v[32:33], v[198:199], v[22:23] op_sel_hi:[1,0]
	v_pk_mul_f32 v[98:99], v[196:197], v[22:23] op_sel_hi:[1,0]
	ds_read_b128 v[196:199], v255 offset:2304
	ds_read_b128 v[204:207], v255 offset:2320
	v_lshlrev_b32_e32 v200, 16, v70
	v_and_b32_e32 v201, 0xffff0000, v70
	v_pk_fma_f32 v[18:19], v[18:19], v[200:201], 0 op_sel_hi:[1,1,0]
	v_lshlrev_b32_e32 v200, 16, v74
	v_and_b32_e32 v201, 0xffff0000, v74
	v_pk_fma_f32 v[18:19], v[28:29], v[200:201], v[18:19]
	v_lshlrev_b32_e32 v28, 16, v58
	v_and_b32_e32 v29, 0xffff0000, v58
	v_pk_fma_f32 v[18:19], v[94:95], v[28:29], v[18:19]
	v_lshlrev_b32_e32 v28, 16, v78
	v_and_b32_e32 v29, 0xffff0000, v78
	v_pk_mul_f32 v[96:97], v[22:23], v[96:97] op_sel_hi:[0,1]
	s_waitcnt lgkmcnt(0)
	v_pk_fma_f32 v[18:19], v[196:197], v[28:29], v[18:19]
	s_nop 0
	v_mul_f32_e32 v23, 0xbfb8aa3b, v18
	v_exp_f32_e32 v23, v23
	s_nop 0
	v_add_f32_e32 v23, 1.0, v23
	v_rcp_f32_e32 v28, v23
	v_mul_f32_e32 v23, 0xbfb8aa3b, v19
	v_exp_f32_e32 v23, v23
	s_nop 0
	v_add_f32_e32 v23, 1.0, v23
	v_rcp_f32_e32 v29, v23
	s_nop 0
	v_pk_mul_f32 v[28:29], v[18:19], v[28:29]
	v_lshlrev_b32_e32 v18, 16, v71
	v_and_b32_e32 v19, 0xffff0000, v71
	v_pk_fma_f32 v[18:19], v[20:21], v[18:19], 0 op_sel_hi:[1,1,0]
	v_lshlrev_b32_e32 v20, 16, v75
	v_and_b32_e32 v21, 0xffff0000, v75
	v_pk_fma_f32 v[18:19], v[30:31], v[20:21], v[18:19]
	v_lshlrev_b32_e32 v20, 16, v59
	v_and_b32_e32 v21, 0xffff0000, v59
	v_pk_fma_f32 v[18:19], v[96:97], v[20:21], v[18:19]
	v_lshlrev_b32_e32 v20, 16, v79
	v_and_b32_e32 v21, 0xffff0000, v79
	v_pk_fma_f32 v[18:19], v[198:199], v[20:21], v[18:19]
	s_nop 0
	v_mul_f32_e32 v20, 0xbfb8aa3b, v18
	v_mul_f32_e32 v21, 0xbfb8aa3b, v19
	v_exp_f32_e32 v20, v20
	v_exp_f32_e32 v21, v21
	v_add_f32_e32 v20, 1.0, v20
	v_add_f32_e32 v21, 1.0, v21
	v_rcp_f32_e32 v20, v20
	v_rcp_f32_e32 v21, v21
	s_nop 0
	v_pk_mul_f32 v[20:21], v[18:19], v[20:21]
	v_lshlrev_b32_e32 v18, 16, v72
	v_and_b32_e32 v19, 0xffff0000, v72
	v_pk_fma_f32 v[10:11], v[10:11], v[18:19], 0 op_sel_hi:[1,1,0]
	v_lshlrev_b32_e32 v18, 16, v76
	v_and_b32_e32 v19, 0xffff0000, v76
	v_pk_fma_f32 v[10:11], v[16:17], v[18:19], v[10:11]
	v_lshlrev_b32_e32 v16, 16, v60
	v_and_b32_e32 v17, 0xffff0000, v60
	v_pk_fma_f32 v[10:11], v[98:99], v[16:17], v[10:11]
	v_lshlrev_b32_e32 v16, 16, v80
	v_and_b32_e32 v17, 0xffff0000, v80
	v_pk_fma_f32 v[10:11], v[204:205], v[16:17], v[10:11]
	s_nop 0
	v_mul_f32_e32 v16, 0xbfb8aa3b, v10
	v_mul_f32_e32 v17, 0xbfb8aa3b, v11
	v_exp_f32_e32 v16, v16
	v_exp_f32_e32 v17, v17
	v_add_f32_e32 v16, 1.0, v16
	v_add_f32_e32 v17, 1.0, v17
	v_rcp_f32_e32 v16, v16
	v_rcp_f32_e32 v17, v17
	s_nop 0
	v_pk_mul_f32 v[30:31], v[10:11], v[16:17]
	v_lshlrev_b32_e32 v10, 16, v73
	v_and_b32_e32 v11, 0xffff0000, v73
	v_pk_fma_f32 v[8:9], v[8:9], v[10:11], 0 op_sel_hi:[1,1,0]
	v_lshlrev_b32_e32 v10, 16, v77
	v_and_b32_e32 v11, 0xffff0000, v77
	v_pk_fma_f32 v[8:9], v[12:13], v[10:11], v[8:9]
	v_lshlrev_b32_e32 v10, 16, v61
	v_and_b32_e32 v11, 0xffff0000, v61
	v_pk_fma_f32 v[8:9], v[32:33], v[10:11], v[8:9]
	v_lshlrev_b32_e32 v10, 16, v81
	v_and_b32_e32 v11, 0xffff0000, v81
	v_pk_fma_f32 v[8:9], v[206:207], v[10:11], v[8:9]
	v_mov_b32_e32 v17, v31
	v_mul_f32_e32 v10, 0xbfb8aa3b, v9
	v_exp_f32_e32 v10, v10
	s_nop 0
	v_add_f32_e32 v10, 1.0, v10
	v_rcp_f32_e32 v11, v10
	v_mul_f32_e32 v10, 0xbfb8aa3b, v8
	v_exp_f32_e32 v10, v10
	s_nop 0
	v_add_f32_e32 v10, 1.0, v10
	v_rcp_f32_e32 v10, v10
	s_nop 0
	v_pk_mul_f32 v[12:13], v[8:9], v[10:11]
	v_mov_b32_e32 v10, v29
	v_mov_b32_e32 v11, v21
	v_mov_b32_e32 v8, v28
	v_mov_b32_e32 v9, v20
	v_pk_mul_f32 v[10:11], v[10:11], v[10:11]
	v_mov_b32_e32 v16, v13
	v_pk_fma_f32 v[8:9], v[8:9], v[8:9], v[10:11]
	v_mov_b32_e32 v10, v12
	v_mov_b32_e32 v11, v30
	v_pk_mul_f32 v[16:17], v[16:17], v[16:17]
	v_add_f32_e32 v8, v8, v9
	v_pk_fma_f32 v[10:11], v[10:11], v[10:11], v[16:17]
	s_nop 0
	v_add_f32_e32 v8, v11, v8
	v_add_f32_e32 v8, v10, v8
	ds_bpermute_b32 v9, v101, v8
	s_waitcnt lgkmcnt(0)
; #define LAS __attribute__((address_space(3)))
; DI float bflo(unsigned w) { return __uint_as_float(w << 16); }
; DI float bfhi(unsigned w) { return __uint_as_float(w & 0xffff0000u); }
;     ...
;     for (int which = 0; which < 3; ++which) {
;         const int t = tid >> 3, cg8 = tid & 7; const int col = which * 512 + h * 64 + cg8 * 8;
;         float acc[8];
; #pragma unroll
;         for (int e = 0; e < 8; ++e) acc[e] = 0.f;
; #pragma unroll
;         for (int j = 0; j < 4; ++j) { const int sp = n * 64 + t - 3 + j; const float ok = sp >= 0 ? 1.f : 0.f;
;             const u32x4 xv = xin[which * 4 + j];
;             const f32x4 w0 = *(const f32x4*)(conv_w + j * 1536 + col) * ok, w1 = *(const f32x4*)(conv_w + j * 1536 + col + 4) * ok;
;             acc[0] += w0[0] * bflo(xv.x); acc[1] += w0[1] * bfhi(xv.x); acc[2] += w0[2] * bflo(xv.y); acc[3] += w0[3] * bfhi(xv.y);
;             acc[4] += w1[0] * bflo(xv.z); acc[5] += w1[1] * bfhi(xv.z); acc[6] += w1[2] * bflo(xv.w); acc[7] += w1[3] * bfhi(xv.w); }
; #pragma unroll
;         for (int e = 0; e < 8; ++e) acc[e] = silu_f(acc[e]);
;         if (which == 2) { LAS float* dst = vc + t * 68 + cg8 * 8; *(LAS f32x4*)dst = (f32x4){acc[0], acc[1], acc[2], acc[3]}; *(LAS f32x4*)(dst + 4) = (f32x4){acc[4], acc[5], acc[6], acc[7]}; }
;         else {
;             float ss = (acc[0] * acc[0] + acc[1] * acc[1]) + (acc[2] * acc[2] + acc[3] * acc[3]) + (acc[4] * acc[4] + acc[5] * acc[5]) + (acc[6] * acc[6] + acc[7] * acc[7]);
;             ss += __shfl_xor(ss, 1); ss += __shfl_xor(ss, 2); ss += __shfl_xor(ss, 4);
;             const float sc = (which ? 1.0f : 0.125f) * __builtin_amdgcn_rsqf(ss + 1e-6f);
;             const f32x4 y0 = (f32x4){acc[0], acc[1], acc[2], acc[3]} * sc, y1 = (f32x4){acc[4], acc[5], acc[6], acc[7]} * sc;
;             LAS float* dst = (which ? kc : qc) + t * 68 + cg8 * 8; *(LAS f32x4*)dst = y0; *(LAS f32x4*)(dst + 4) = y1;
;             u32x4 hh; hh.x = pk2(y0[0], y0[1]); hh.y = pk2(y0[2], y0[3]); hh.z = pk2(y1[0], y1[1]); hh.w = pk2(y1[2], y1[3]);
;             u32x4 lo; lo.x = pk2(y0[0] - bflo(hh.x), y0[1] - bfhi(hh.x)); lo.y = pk2(y0[2] - bflo(hh.y), y0[3] - bfhi(hh.y)); lo.z = pk2(y1[0] - bflo(hh.z), y1[1] - bfhi(hh.z)); lo.w = pk2(y1[2] - bflo(hh.w), y1[3] - bfhi(hh.w));
;             *(LAS u32x4*)((which ? KH : QH) + t * 72 + cg8 * 8) = hh; *(LAS u32x4*)((which ? KL : QL) + t * 72 + cg8 * 8) = lo; }
	v_add_f32_e32 v8, v8, v9
	ds_bpermute_b32 v9, v102, v8
	s_waitcnt lgkmcnt(0)
	v_add_f32_e32 v8, v8, v9
	ds_bpermute_b32 v9, v103, v8
	s_waitcnt lgkmcnt(0)
	v_add_f32_e32 v8, v8, v9
	v_add_f32_e32 v8, 0x358637bd, v8
	v_rsq_f32_e32 v8, v8
	s_nop 0
	v_mul_f32_e32 v32, 0x3e000000, v8
	v_pk_mul_f32 v[10:11], v[20:21], v[32:33] op_sel_hi:[1,0]
	v_pk_mul_f32 v[8:9], v[28:29], v[32:33] op_sel_hi:[1,0]
	v_pk_mul_f32 v[18:19], v[12:13], v[32:33] op_sel_hi:[1,0]
	v_pk_mul_f32 v[16:17], v[30:31], v[32:33] op_sel_hi:[1,0]
	ds_write_b128 v112, v[8:11]
	ds_write_b128 v112, v[16:19] offset:16
	v_cvt_pk_bf16_f32 v8, v8, v9
	v_cvt_pk_bf16_f32 v9, v10, v11
	v_cvt_pk_bf16_f32 v10, v16, v17
	v_cvt_pk_bf16_f32 v11, v18, v19
	v_lshlrev_b32_e32 v16, 16, v8
	v_and_b32_e32 v17, 0xffff0000, v8
	v_lshlrev_b32_e32 v18, 16, v9
	v_and_b32_e32 v19, 0xffff0000, v9
	v_pk_fma_f32 v[16:17], v[28:29], v[32:33], v[16:17] op_sel_hi:[1,0,1] neg_lo:[0,0,1] neg_hi:[0,0,1]
	v_pk_fma_f32 v[18:19], v[20:21], v[32:33], v[18:19] op_sel_hi:[1,0,1] neg_lo:[0,0,1] neg_hi:[0,0,1]
	v_cvt_pk_bf16_f32 v16, v16, v17
	v_cvt_pk_bf16_f32 v17, v18, v19
	v_lshlrev_b32_e32 v18, 16, v10
	v_and_b32_e32 v19, 0xffff0000, v10
	v_lshlrev_b32_e32 v20, 16, v11
	v_and_b32_e32 v21, 0xffff0000, v11
	v_pk_fma_f32 v[18:19], v[30:31], v[32:33], v[18:19] op_sel_hi:[1,0,1] neg_lo:[0,0,1] neg_hi:[0,0,1]
	v_pk_fma_f32 v[12:13], v[12:13], v[32:33], v[20:21] op_sel_hi:[1,0,1] neg_lo:[0,0,1] neg_hi:[0,0,1]
	v_cvt_pk_bf16_f32 v18, v18, v19
	v_cvt_pk_bf16_f32 v19, v12, v13
	ds_write_b128 v113, v[8:11]
	ds_write_b128 v114, v[16:19]
	ds_read_b128 v[8:11], v255 offset:256
	ds_read_b128 v[16:19], v255 offset:272
	s_waitcnt lgkmcnt(0)
	v_pk_mul_f32 v[8:9], v[26:27], v[8:9] op_sel_hi:[0,1]
	s_waitcnt lgkmcnt(0)
	v_pk_mul_f32 v[32:33], v[26:27], v[16:17] op_sel_hi:[0,1]
	v_lshl_add_u64 v[16:17], v[14:15], 0, s[16:17]
	s_movk_i32 s16, 0x2000
	v_add_co_u32_e32 v98, vcc, s16, v14
	v_pk_mul_f32 v[12:13], v[26:27], v[18:19] op_sel_hi:[0,1]
	s_nop 0
	v_addc_co_u32_e32 v99, vcc, 0, v15, vcc
	ds_read_b128 v[18:21], v255 offset:1024
	ds_read_b128 v[28:31], v255 offset:1040
	s_mov_b64 s[16:17], 0x3800
	v_lshl_add_u64 v[16:17], v[14:15], 0, s[16:17]
	s_mov_b64 s[16:17], 0x5000
	v_lshl_add_u64 v[196:197], v[14:15], 0, s[16:17]
	s_movk_i32 s16, 0x5000
	v_pk_fma_f32 v[8:9], v[8:9], v[208:209], 0 op_sel_hi:[1,1,0]
	v_lshlrev_b32_e32 v208, 16, v62
	v_and_b32_e32 v209, 0xffff0000, v62
	v_pk_mul_f32 v[10:11], v[26:27], v[10:11] op_sel_hi:[0,1]
	s_waitcnt lgkmcnt(0)
	v_pk_mul_f32 v[18:19], v[24:25], v[18:19] op_sel_hi:[0,1]
	s_waitcnt lgkmcnt(0)
	v_pk_mul_f32 v[200:201], v[24:25], v[30:31] op_sel_hi:[0,1]
	v_pk_mul_f32 v[204:205], v[24:25], v[28:29] op_sel_hi:[0,1]
	ds_read_b128 v[28:31], v255 offset:1792
	ds_read_b128 v[94:97], v255 offset:1808
	v_add_co_u32_e32 v16, vcc, s16, v14
	v_pk_fma_f32 v[8:9], v[18:19], v[208:209], v[8:9]
	s_nop 0
	v_addc_co_u32_e32 v17, vcc, 0, v15, vcc
	v_lshlrev_b32_e32 v18, 16, v50
	v_and_b32_e32 v19, 0xffff0000, v50
	v_pk_mul_f32 v[20:21], v[24:25], v[20:21] op_sel_hi:[0,1]
	s_mov_b64 s[16:17], 0x1000
	s_andn2_b64 vcc, exec, s[46:47]
	s_waitcnt lgkmcnt(0)
	v_pk_mul_f32 v[28:29], v[22:23], v[28:29] op_sel_hi:[0,1]
	s_waitcnt lgkmcnt(0)
	v_pk_mul_f32 v[6:7], v[22:23], v[96:97] op_sel_hi:[0,1]
	v_pk_mul_f32 v[206:207], v[22:23], v[94:95] op_sel_hi:[0,1]
	ds_read_b128 v[94:97], v255 offset:2560
	s_nop 0
	ds_read_b128 v[196:199], v255 offset:2576
	v_pk_fma_f32 v[8:9], v[28:29], v[18:19], v[8:9]
	v_lshlrev_b32_e32 v18, 16, v66
	v_and_b32_e32 v19, 0xffff0000, v66
	v_pk_mul_f32 v[30:31], v[22:23], v[30:31] op_sel_hi:[0,1]
	s_waitcnt lgkmcnt(0)
	v_pk_fma_f32 v[8:9], v[94:95], v[18:19], v[8:9]
	s_nop 0
	v_mul_f32_e32 v18, 0xbfb8aa3b, v8
	v_mul_f32_e32 v19, 0xbfb8aa3b, v9
	v_exp_f32_e32 v18, v18
	v_exp_f32_e32 v19, v19
	v_add_f32_e32 v18, 1.0, v18
	v_add_f32_e32 v19, 1.0, v19
	v_rcp_f32_e32 v18, v18
	v_rcp_f32_e32 v19, v19
	s_nop 0
	v_pk_mul_f32 v[18:19], v[8:9], v[18:19]
	v_lshlrev_b32_e32 v8, 16, v55
	v_and_b32_e32 v9, 0xffff0000, v55
	v_pk_fma_f32 v[8:9], v[10:11], v[8:9], 0 op_sel_hi:[1,1,0]
	v_lshlrev_b32_e32 v10, 16, v63
	v_and_b32_e32 v11, 0xffff0000, v63
	v_pk_fma_f32 v[8:9], v[20:21], v[10:11], v[8:9]
	v_lshlrev_b32_e32 v10, 16, v51
	v_and_b32_e32 v11, 0xffff0000, v51
	v_pk_fma_f32 v[8:9], v[30:31], v[10:11], v[8:9]
	v_lshlrev_b32_e32 v10, 16, v67
	v_and_b32_e32 v11, 0xffff0000, v67
	v_pk_fma_f32 v[8:9], v[96:97], v[10:11], v[8:9]
	s_nop 0
	v_mul_f32_e32 v10, 0xbfb8aa3b, v8
	v_mul_f32_e32 v11, 0xbfb8aa3b, v9
	v_exp_f32_e32 v10, v10
	v_exp_f32_e32 v11, v11
	v_add_f32_e32 v10, 1.0, v10
	v_add_f32_e32 v11, 1.0, v11
	v_rcp_f32_e32 v10, v10
	v_rcp_f32_e32 v11, v11
	s_nop 0
	v_pk_mul_f32 v[20:21], v[8:9], v[10:11]
	v_lshlrev_b32_e32 v8, 16, v56
	v_and_b32_e32 v9, 0xffff0000, v56
	v_pk_fma_f32 v[8:9], v[32:33], v[8:9], 0 op_sel_hi:[1,1,0]
	v_lshlrev_b32_e32 v10, 16, v64
	v_and_b32_e32 v11, 0xffff0000, v64
	v_pk_fma_f32 v[8:9], v[204:205], v[10:11], v[8:9]
	v_lshlrev_b32_e32 v10, 16, v52
	v_and_b32_e32 v11, 0xffff0000, v52
	v_pk_fma_f32 v[8:9], v[206:207], v[10:11], v[8:9]
	v_lshlrev_b32_e32 v10, 16, v68
	v_and_b32_e32 v11, 0xffff0000, v68
	s_waitcnt lgkmcnt(0)
; #define LAS __attribute__((address_space(3)))
; DI float bflo(unsigned w) { return __uint_as_float(w << 16); }
; DI float bfhi(unsigned w) { return __uint_as_float(w & 0xffff0000u); }
;     ...
;     for (int which = 0; which < 3; ++which) {
;         const int t = tid >> 3, cg8 = tid & 7; const int col = which * 512 + h * 64 + cg8 * 8;
;         float acc[8];
; #pragma unroll
;         for (int e = 0; e < 8; ++e) acc[e] = 0.f;
; #pragma unroll
;         for (int j = 0; j < 4; ++j) { const int sp = n * 64 + t - 3 + j; const float ok = sp >= 0 ? 1.f : 0.f;
;             const u32x4 xv = xin[which * 4 + j];
;             const f32x4 w0 = *(const f32x4*)(conv_w + j * 1536 + col) * ok, w1 = *(const f32x4*)(conv_w + j * 1536 + col + 4) * ok;
;             acc[0] += w0[0] * bflo(xv.x); acc[1] += w0[1] * bfhi(xv.x); acc[2] += w0[2] * bflo(xv.y); acc[3] += w0[3] * bfhi(xv.y);
;             acc[4] += w1[0] * bflo(xv.z); acc[5] += w1[1] * bfhi(xv.z); acc[6] += w1[2] * bflo(xv.w); acc[7] += w1[3] * bfhi(xv.w); }
; #pragma unroll
;         for (int e = 0; e < 8; ++e) acc[e] = silu_f(acc[e]);
;         if (which == 2) { LAS float* dst = vc + t * 68 + cg8 * 8; *(LAS f32x4*)dst = (f32x4){acc[0], acc[1], acc[2], acc[3]}; *(LAS f32x4*)(dst + 4) = (f32x4){acc[4], acc[5], acc[6], acc[7]}; }
;         else {
;             float ss = (acc[0] * acc[0] + acc[1] * acc[1]) + (acc[2] * acc[2] + acc[3] * acc[3]) + (acc[4] * acc[4] + acc[5] * acc[5]) + (acc[6] * acc[6] + acc[7] * acc[7]);
;             ss += __shfl_xor(ss, 1); ss += __shfl_xor(ss, 2); ss += __shfl_xor(ss, 4);
;             const float sc = (which ? 1.0f : 0.125f) * __builtin_amdgcn_rsqf(ss + 1e-6f);
;             const f32x4 y0 = (f32x4){acc[0], acc[1], acc[2], acc[3]} * sc, y1 = (f32x4){acc[4], acc[5], acc[6], acc[7]} * sc;
;             LAS float* dst = (which ? kc : qc) + t * 68 + cg8 * 8; *(LAS f32x4*)dst = y0; *(LAS f32x4*)(dst + 4) = y1;
;             u32x4 hh; hh.x = pk2(y0[0], y0[1]); hh.y = pk2(y0[2], y0[3]); hh.z = pk2(y1[0], y1[1]); hh.w = pk2(y1[2], y1[3]);
;             u32x4 lo; lo.x = pk2(y0[0] - bflo(hh.x), y0[1] - bfhi(hh.x)); lo.y = pk2(y0[2] - bflo(hh.y), y0[3] - bfhi(hh.y)); lo.z = pk2(y1[0] - bflo(hh.z), y1[1] - bfhi(hh.z)); lo.w = pk2(y1[2] - bflo(hh.w), y1[3] - bfhi(hh.w));
;             *(LAS u32x4*)((which ? KH : QH) + t * 72 + cg8 * 8) = hh; *(LAS u32x4*)((which ? KL : QL) + t * 72 + cg8 * 8) = lo; }
	v_pk_fma_f32 v[8:9], v[196:197], v[10:11], v[8:9]
	s_nop 0
	v_mul_f32_e32 v10, 0xbfb8aa3b, v8
	v_mul_f32_e32 v11, 0xbfb8aa3b, v9
	v_exp_f32_e32 v10, v10
	v_exp_f32_e32 v11, v11
	v_add_f32_e32 v10, 1.0, v10
	v_add_f32_e32 v11, 1.0, v11
	v_rcp_f32_e32 v10, v10
	v_rcp_f32_e32 v11, v11
	s_nop 0
	v_pk_mul_f32 v[28:29], v[8:9], v[10:11]
	v_lshlrev_b32_e32 v8, 16, v57
	v_and_b32_e32 v9, 0xffff0000, v57
	v_pk_fma_f32 v[8:9], v[12:13], v[8:9], 0 op_sel_hi:[1,1,0]
	v_lshlrev_b32_e32 v10, 16, v65
	v_and_b32_e32 v11, 0xffff0000, v65
	v_pk_fma_f32 v[8:9], v[200:201], v[10:11], v[8:9]
	v_lshlrev_b32_e32 v10, 16, v53
	v_and_b32_e32 v11, 0xffff0000, v53
	v_pk_fma_f32 v[6:7], v[6:7], v[10:11], v[8:9]
	v_lshlrev_b32_e32 v8, 16, v69
	v_and_b32_e32 v9, 0xffff0000, v69
	v_pk_fma_f32 v[6:7], v[198:199], v[8:9], v[6:7]
	v_mov_b32_e32 v11, v29
	v_mul_f32_e32 v8, 0xbfb8aa3b, v7
	v_exp_f32_e32 v8, v8
	s_nop 0
	v_add_f32_e32 v8, 1.0, v8
	v_rcp_f32_e32 v9, v8
	v_mul_f32_e32 v8, 0xbfb8aa3b, v6
	v_exp_f32_e32 v8, v8
	s_nop 0
	v_add_f32_e32 v8, 1.0, v8
	v_rcp_f32_e32 v8, v8
	s_nop 0
	v_pk_mul_f32 v[30:31], v[6:7], v[8:9]
	v_mov_b32_e32 v8, v19
	v_mov_b32_e32 v9, v21
	v_mov_b32_e32 v6, v18
	v_mov_b32_e32 v7, v20
	v_pk_mul_f32 v[8:9], v[8:9], v[8:9]
	v_mov_b32_e32 v10, v31
	v_pk_fma_f32 v[6:7], v[6:7], v[6:7], v[8:9]
	v_mov_b32_e32 v8, v30
	v_mov_b32_e32 v9, v28
	v_pk_mul_f32 v[10:11], v[10:11], v[10:11]
	v_add_f32_e32 v6, v6, v7
	v_pk_fma_f32 v[8:9], v[8:9], v[8:9], v[10:11]
	s_nop 0
	v_add_f32_e32 v6, v9, v6
	v_add_f32_e32 v6, v8, v6
	ds_bpermute_b32 v7, v101, v6
	s_waitcnt lgkmcnt(0)
	v_add_f32_e32 v6, v6, v7
	ds_bpermute_b32 v7, v102, v6
	s_waitcnt lgkmcnt(0)
	v_add_f32_e32 v6, v6, v7
	ds_bpermute_b32 v7, v103, v6
	s_waitcnt lgkmcnt(0)
	v_add_f32_e32 v6, v6, v7
	v_add_f32_e32 v6, 0x358637bd, v6
	v_rsq_f32_e32 v32, v6
	s_nop 0
	v_pk_mul_f32 v[8:9], v[20:21], v[32:33] op_sel_hi:[1,0]
	v_pk_mul_f32 v[6:7], v[18:19], v[32:33] op_sel_hi:[1,0]
	v_pk_mul_f32 v[12:13], v[30:31], v[32:33] op_sel_hi:[1,0]
	v_pk_mul_f32 v[10:11], v[28:29], v[32:33] op_sel_hi:[1,0]
	ds_write_b128 v112, v[6:9] offset:17408
	ds_write_b128 v112, v[10:13] offset:17424
	v_cvt_pk_bf16_f32 v6, v6, v7
	v_cvt_pk_bf16_f32 v7, v8, v9
	v_cvt_pk_bf16_f32 v8, v10, v11
	v_cvt_pk_bf16_f32 v9, v12, v13
	v_lshlrev_b32_e32 v10, 16, v6
	v_and_b32_e32 v11, 0xffff0000, v6
	v_lshlrev_b32_e32 v12, 16, v7
	v_and_b32_e32 v13, 0xffff0000, v7
	v_pk_fma_f32 v[10:11], v[18:19], v[32:33], v[10:11] op_sel_hi:[1,0,1] neg_lo:[0,0,1] neg_hi:[0,0,1]
	v_pk_fma_f32 v[12:13], v[20:21], v[32:33], v[12:13] op_sel_hi:[1,0,1] neg_lo:[0,0,1] neg_hi:[0,0,1]
	v_cvt_pk_bf16_f32 v10, v10, v11
	v_cvt_pk_bf16_f32 v11, v12, v13
	v_lshlrev_b32_e32 v12, 16, v8
	v_and_b32_e32 v13, 0xffff0000, v8
	v_lshlrev_b32_e32 v18, 16, v9
	v_and_b32_e32 v19, 0xffff0000, v9
	v_pk_fma_f32 v[12:13], v[28:29], v[32:33], v[12:13] op_sel_hi:[1,0,1] neg_lo:[0,0,1] neg_hi:[0,0,1]
	v_pk_fma_f32 v[18:19], v[30:31], v[32:33], v[18:19] op_sel_hi:[1,0,1] neg_lo:[0,0,1] neg_hi:[0,0,1]
	v_cvt_pk_bf16_f32 v12, v12, v13
	v_cvt_pk_bf16_f32 v13, v18, v19
	ds_write_b128 v115, v[6:9]
	ds_write_b128 v116, v[10:13]
	v_lshl_add_u64 v[10:11], v[14:15], 0, s[16:17]
	ds_read_b128 v[6:9], v255 offset:512
	s_nop 0
	ds_read_b128 v[10:13], v255 offset:528
	s_mov_b64 s[16:17], 0x2800
	v_lshl_add_u64 v[2:3], v[14:15], 0, s[16:17]
	s_mov_b64 s[16:17], 0x5800
	s_waitcnt lgkmcnt(0)
	v_pk_mul_f32 v[6:7], v[26:27], v[6:7] op_sel_hi:[0,1]
	s_waitcnt lgkmcnt(0)
	v_pk_mul_f32 v[28:29], v[26:27], v[12:13] op_sel_hi:[0,1]
	v_pk_mul_f32 v[94:95], v[26:27], v[10:11] op_sel_hi:[0,1]
	ds_read_b128 v[10:13], v255 offset:1280
	ds_read_b128 v[18:21], v255 offset:1296
	v_pk_mul_f32 v[8:9], v[26:27], v[8:9] op_sel_hi:[0,1]
	s_waitcnt lgkmcnt(0)
	v_pk_mul_f32 v[10:11], v[24:25], v[10:11] op_sel_hi:[0,1]
	s_waitcnt lgkmcnt(0)
	v_pk_mul_f32 v[96:97], v[24:25], v[18:19] op_sel_hi:[0,1]
	v_lshl_add_u64 v[18:19], v[14:15], 0, s[62:63]
	v_pk_mul_f32 v[30:31], v[24:25], v[20:21] op_sel_hi:[0,1]
	ds_read_b128 v[2:5], v255 offset:2048
	s_nop 0
	ds_read_b128 v[18:21], v255 offset:2064
	v_pk_mul_f32 v[12:13], v[24:25], v[12:13] op_sel_hi:[0,1]
	s_waitcnt lgkmcnt(0)
	v_pk_mul_f32 v[4:5], v[22:23], v[4:5] op_sel_hi:[0,1]
	s_waitcnt lgkmcnt(0)
	v_pk_mul_f32 v[98:99], v[22:23], v[18:19] op_sel_hi:[0,1]
	v_lshl_add_u64 v[18:19], v[14:15], 0, s[16:17]
	v_pk_mul_f32 v[32:33], v[22:23], v[20:21] op_sel_hi:[0,1]
	ds_read_b128 v[14:17], v255 offset:2816
	s_nop 0
	ds_read_b128 v[18:21], v255 offset:2832
	v_pk_mul_f32 v[2:3], v[22:23], v[2:3] op_sel_hi:[0,1]
	v_lshlrev_b32_e32 v22, 16, v34
	v_and_b32_e32 v23, 0xffff0000, v34
	v_pk_fma_f32 v[6:7], v[6:7], v[22:23], 0 op_sel_hi:[1,1,0]
	v_lshlrev_b32_e32 v22, 16, v38
	v_and_b32_e32 v23, 0xffff0000, v38
	v_pk_fma_f32 v[6:7], v[10:11], v[22:23], v[6:7]
	v_lshlrev_b32_e32 v10, 16, v42
	v_and_b32_e32 v11, 0xffff0000, v42
	v_pk_fma_f32 v[2:3], v[2:3], v[10:11], v[6:7]
	v_lshlrev_b32_e32 v10, 16, v35
	v_and_b32_e32 v11, 0xffff0000, v35
	v_pk_fma_f32 v[8:9], v[8:9], v[10:11], 0 op_sel_hi:[1,1,0]
	v_lshlrev_b32_e32 v10, 16, v39
	v_and_b32_e32 v11, 0xffff0000, v39
	v_lshlrev_b32_e32 v6, 16, v46
	v_and_b32_e32 v7, 0xffff0000, v46
	v_pk_fma_f32 v[8:9], v[12:13], v[10:11], v[8:9]
	v_lshlrev_b32_e32 v10, 16, v43
	v_and_b32_e32 v11, 0xffff0000, v43
	v_pk_fma_f32 v[4:5], v[4:5], v[10:11], v[8:9]
	v_lshlrev_b32_e32 v8, 16, v47
	v_and_b32_e32 v9, 0xffff0000, v47
	v_lshlrev_b32_e32 v10, 16, v37
	v_and_b32_e32 v11, 0xffff0000, v37
	v_pk_fma_f32 v[10:11], v[28:29], v[10:11], 0 op_sel_hi:[1,1,0]
	v_lshlrev_b32_e32 v12, 16, v41
	v_and_b32_e32 v13, 0xffff0000, v41
	v_pk_fma_f32 v[10:11], v[30:31], v[12:13], v[10:11]
	v_lshlrev_b32_e32 v12, 16, v45
	v_and_b32_e32 v13, 0xffff0000, v45
	v_pk_fma_f32 v[10:11], v[32:33], v[12:13], v[10:11]
	v_lshlrev_b32_e32 v12, 16, v49
	v_and_b32_e32 v13, 0xffff0000, v49
	s_waitcnt lgkmcnt(0)
; #define LAS __attribute__((address_space(3)))
; DI float bflo(unsigned w) { return __uint_as_float(w << 16); }
; DI float bfhi(unsigned w) { return __uint_as_float(w & 0xffff0000u); }
; DI float silu_f(float g) { return g * frcp(1.f + fexp2(-1.4426950408889634f * g)); }
;     ...
;         for (int j = 0; j < 4; ++j) { const int sp = n * 64 + t - 3 + j; const float ok = sp >= 0 ? 1.f : 0.f;
;             const u32x4 xv = xin[which * 4 + j];
;             const f32x4 w0 = *(const f32x4*)(conv_w + j * 1536 + col) * ok, w1 = *(const f32x4*)(conv_w + j * 1536 + col + 4) * ok;
;             acc[0] += w0[0] * bflo(xv.x); acc[1] += w0[1] * bfhi(xv.x); acc[2] += w0[2] * bflo(xv.y); acc[3] += w0[3] * bfhi(xv.y);
;             acc[4] += w1[0] * bflo(xv.z); acc[5] += w1[1] * bfhi(xv.z); acc[6] += w1[2] * bflo(xv.w); acc[7] += w1[3] * bfhi(xv.w); }
; #pragma unroll
;         for (int e = 0; e < 8; ++e) acc[e] = silu_f(acc[e]);
;         if (which == 2) { LAS float* dst = vc + t * 68 + cg8 * 8; *(LAS f32x4*)dst = (f32x4){acc[0], acc[1], acc[2], acc[3]}; *(LAS f32x4*)(dst + 4) = (f32x4){acc[4], acc[5], acc[6], acc[7]}; }
	v_pk_fma_f32 v[2:3], v[14:15], v[6:7], v[2:3]
	s_nop 0
	v_mul_f32_e32 v6, 0xbfb8aa3b, v2
	v_mul_f32_e32 v7, 0xbfb8aa3b, v3
	v_pk_fma_f32 v[4:5], v[16:17], v[8:9], v[4:5]
	v_exp_f32_e32 v6, v6
	v_exp_f32_e32 v7, v7
	v_mul_f32_e32 v8, 0xbfb8aa3b, v4
	v_mul_f32_e32 v9, 0xbfb8aa3b, v5
	v_exp_f32_e32 v8, v8
	v_exp_f32_e32 v9, v9
	v_add_f32_e32 v6, 1.0, v6
	v_add_f32_e32 v7, 1.0, v7
	v_rcp_f32_e32 v6, v6
	v_rcp_f32_e32 v7, v7
	v_add_f32_e32 v8, 1.0, v8
	v_add_f32_e32 v9, 1.0, v9
	v_rcp_f32_e32 v8, v8
	v_rcp_f32_e32 v9, v9
	s_waitcnt lgkmcnt(0)
	v_pk_fma_f32 v[10:11], v[20:21], v[12:13], v[10:11]
	v_pk_mul_f32 v[2:3], v[2:3], v[6:7]
	v_mul_f32_e32 v12, 0xbfb8aa3b, v11
	v_lshlrev_b32_e32 v6, 16, v36
	v_and_b32_e32 v7, 0xffff0000, v36
	v_exp_f32_e32 v12, v12
	v_pk_mul_f32 v[4:5], v[4:5], v[8:9]
	v_pk_fma_f32 v[6:7], v[94:95], v[6:7], 0 op_sel_hi:[1,1,0]
	v_lshlrev_b32_e32 v8, 16, v40
	v_and_b32_e32 v9, 0xffff0000, v40
	v_pk_fma_f32 v[6:7], v[96:97], v[8:9], v[6:7]
	v_lshlrev_b32_e32 v8, 16, v44
	v_and_b32_e32 v9, 0xffff0000, v44
	v_pk_fma_f32 v[6:7], v[98:99], v[8:9], v[6:7]
	v_lshlrev_b32_e32 v8, 16, v48
	v_and_b32_e32 v9, 0xffff0000, v48
	v_pk_fma_f32 v[6:7], v[18:19], v[8:9], v[6:7]
	v_add_f32_e32 v12, 1.0, v12
	v_mul_f32_e32 v8, 0xbfb8aa3b, v6
	v_mul_f32_e32 v9, 0xbfb8aa3b, v7
	v_rcp_f32_e32 v13, v12
	v_mul_f32_e32 v12, 0xbfb8aa3b, v10
	v_exp_f32_e32 v8, v8
	v_exp_f32_e32 v9, v9
	v_exp_f32_e32 v12, v12
	v_add_f32_e32 v8, 1.0, v8
	v_add_f32_e32 v9, 1.0, v9
	v_add_f32_e32 v12, 1.0, v12
	v_rcp_f32_e32 v8, v8
	v_rcp_f32_e32 v9, v9
	v_rcp_f32_e32 v12, v12
	v_pk_mul_f32 v[6:7], v[6:7], v[8:9]
	v_pk_mul_f32 v[8:9], v[10:11], v[12:13]
	ds_write_b128 v176, v[2:5] offset:34816
	ds_write_b128 v176, v[6:9] offset:34832
	s_cbranch_vccnz .LBB0_1747
; DI float bf2f(bf16_t u) { return __uint_as_float(((unsigned)u) << 16); }
;     ...
;     { const float ga = bf2f(gain), gb = bf2f(gbin);
;         const float x = ga + dt_bias[h]; const float sp = fmaxf(x, 0.f) + log1pf(expf(-fabsf(x)));
;         float gv = -expf(a_log[h]) * sp; const float bv = 1.f / (1.f + expf(-gb));
;         if (wid == 0) {
; #pragma unroll
;             for (int o = 1; o < 64; o <<= 1) { const float tt = __shfl_up(gv, o); if (lane >= o) gv += tt; }
;             gcs[lane] = gv; bet[lane] = bv; } }
	s_lshl_b32 s16, s24, 2
	v_mov_b32_e32 v2, s16
	v_readlane_b32 s4, v247, 9
	s_waitcnt vmcnt(0)
	v_mov_b32_e32 v3, v252
	v_readlane_b32 s5, v247, 10
	v_lshlrev_b32_e32 v5, 16, v1
	v_readlane_b32 s16, v247, 21
	s_mov_b32 s16, 0xb2a5705f
	v_readlane_b32 s17, v247, 22
	v_readlane_b32 s6, v247, 11
	v_mov_b32_e32 v4, v253
	v_lshlrev_b32_e32 v2, 16, v100
	v_mul_f32_e32 v6, 0xbfb8aa3b, v2
	v_rndne_f32_e32 v7, v6
	v_fma_f32 v8, v2, s23, -v6
	v_sub_f32_e32 v6, v6, v7
	v_fmac_f32_e32 v8, 0xb2a5705f, v2
	v_add_f32_e32 v6, v6, v8
	v_cvt_i32_f32_e32 v7, v7
	v_exp_f32_e32 v6, v6
	v_readlane_b32 s7, v247, 12
	v_readlane_b32 s8, v247, 13
	v_readlane_b32 s9, v247, 14
	v_ldexp_f32 v6, v6, v7
	v_readlane_b32 s10, v247, 15
	v_readlane_b32 s11, v247, 16
	v_readlane_b32 s12, v247, 17
	v_readlane_b32 s13, v247, 18
	v_readlane_b32 s14, v247, 19
	v_readlane_b32 s15, v247, 20
	v_readlane_b32 s18, v247, 23
	v_readlane_b32 s19, v247, 24
	s_waitcnt vmcnt(1)
	v_mul_f32_e32 v8, 0x3fb8aa3b, v3
	v_rndne_f32_e32 v9, v8
	v_cmp_ngt_f32_e32 vcc, s3, v3
	s_waitcnt vmcnt(0)
	v_add_f32_e32 v4, v4, v5
	v_fma_f32 v5, v3, s2, -v8
	v_mul_f32_e64 v10, |v4|, s23
	v_fmac_f32_e32 v5, 0x32a5705f, v3
	v_sub_f32_e32 v8, v8, v9
	v_fma_f32 v12, |v4|, s23, -v10
	v_rndne_f32_e32 v13, v10
	v_add_f32_e32 v5, v8, v5
	v_cvt_i32_f32_e32 v9, v9
	v_fma_f32 v8, |v4|, s16, v12
	v_sub_f32_e32 v10, v10, v13
	v_exp_f32_e32 v5, v5
	v_add_f32_e32 v8, v10, v8
	v_cvt_i32_f32_e32 v12, v13
	v_exp_f32_e32 v8, v8
	v_ldexp_f32 v5, v5, v9
	v_cndmask_b32_e32 v5, 0, v5, vcc
	v_cmp_nlt_f32_e32 vcc, s64, v3
	v_ldexp_f32 v8, v8, v12
	v_max_f32_e32 v11, 0, v4
	v_cndmask_b32_e32 v3, v193, v5, vcc
	v_cmp_ngt_f32_e64 vcc, |v4|, s96
	s_mov_b32 s16, 0x3f2aaaab
	s_nop 0
	v_cndmask_b32_e32 v5, 0, v8, vcc
	v_cmp_nlt_f32_e64 vcc, |v4|, s97
	s_nop 1
	v_cndmask_b32_e32 v8, v193, v5, vcc
	v_add_f32_e32 v9, 1.0, v8
	v_cvt_f64_f32_e32 v[4:5], v9
	v_frexp_mant_f32_e32 v10, v9
	v_add_f32_e32 v12, -1.0, v9
	v_frexp_exp_i32_f64_e32 v4, v[4:5]
	v_cmp_gt_f32_e32 vcc, s16, v10
	v_sub_f32_e32 v5, v8, v12
	v_sub_f32_e32 v12, v12, v9
	v_subbrev_co_u32_e32 v4, vcc, 0, v4, vcc
	v_add_f32_e32 v10, 1.0, v12
	v_cvt_f32_i32_e32 v12, v4
	v_sub_u32_e32 v4, 0, v4
	v_add_f32_e32 v5, v5, v10
	v_ldexp_f32 v9, v9, v4
	v_ldexp_f32 v4, v5, v4
	v_add_f32_e32 v5, -1.0, v9
	v_add_f32_e32 v10, 1.0, v9
	v_add_f32_e32 v13, 1.0, v5
	v_add_f32_e32 v14, -1.0, v10
	v_mul_f32_e32 v15, 0x3f317218, v12
	v_sub_f32_e32 v13, v9, v13
	v_sub_f32_e32 v9, v9, v14
	s_mov_b32 s16, 0x3f317218
	v_fma_f32 v14, v12, s16, -v15
	v_add_f32_e32 v13, v4, v13
	v_add_f32_e32 v4, v4, v9
	v_fmac_f32_e32 v14, 0xb102e308, v12
	v_add_f32_e32 v12, v10, v4
	v_rcp_f32_e32 v17, v12
	v_add_f32_e32 v9, v5, v13
	v_add_f32_e32 v16, v15, v14
	v_sub_f32_e32 v10, v10, v12
	v_sub_f32_e32 v5, v5, v9
	v_add_f32_e32 v4, v4, v10
	v_add_f32_e32 v5, v13, v5
	v_sub_f32_e32 v10, v16, v15
	v_mul_f32_e32 v13, v9, v17
	v_sub_f32_e32 v10, v14, v10
	v_mul_f32_e32 v14, v12, v13
	v_fma_f32 v15, v13, v12, -v14
	v_fmac_f32_e32 v15, v13, v4
	v_add_f32_e32 v18, v14, v15
	v_sub_f32_e32 v19, v9, v18
	v_sub_f32_e32 v9, v9, v19
	v_sub_f32_e32 v14, v18, v14
	v_sub_f32_e32 v9, v9, v18
	v_sub_f32_e32 v14, v14, v15
	v_add_f32_e32 v5, v5, v9
	v_add_f32_e32 v5, v14, v5
	v_add_f32_e32 v9, v19, v5
	v_mul_f32_e32 v14, v17, v9
	v_sub_f32_e32 v15, v19, v9
	v_mul_f32_e32 v19, v12, v14
	v_fma_f32 v12, v14, v12, -v19
	v_add_f32_e32 v18, v13, v14
	v_fmac_f32_e32 v12, v14, v4
	v_sub_f32_e32 v13, v18, v13
	v_add_f32_e32 v4, v19, v12
	v_sub_f32_e32 v13, v14, v13
	v_sub_f32_e32 v14, v9, v4
	v_sub_f32_e32 v9, v9, v14
	v_add_f32_e32 v5, v5, v15
	v_sub_f32_e32 v15, v4, v19
	v_sub_f32_e32 v4, v9, v4
	v_sub_f32_e32 v12, v15, v12
	v_add_f32_e32 v4, v5, v4
	v_add_f32_e32 v4, v12, v4
	v_add_f32_e32 v4, v14, v4
	v_mul_f32_e32 v4, v17, v4
	v_add_f32_e32 v4, v13, v4
	v_add_f32_e32 v5, v18, v4
	v_mul_f32_e32 v12, v5, v5
	v_fmamk_f32 v14, v12, 0x3e9b6dac, v177
	v_ldexp_f32 v9, v5, 1
	v_sub_f32_e32 v13, v5, v18
	v_mul_f32_e32 v5, v5, v12
	v_fmaak_f32 v12, v12, v14, 0x3f2aaada
	v_mul_f32_e32 v5, v5, v12
	v_add_f32_e32 v12, v9, v5
	v_sub_f32_e32 v4, v4, v13
	v_sub_f32_e32 v9, v12, v9
	v_ldexp_f32 v4, v4, 1
	v_sub_f32_e32 v5, v5, v9
	v_add_f32_e32 v4, v4, v5
	v_add_f32_e32 v5, v12, v4
	v_add_f32_e32 v9, v16, v5
	v_sub_f32_e32 v12, v5, v12
	v_sub_f32_e32 v4, v4, v12
	v_sub_f32_e32 v12, v9, v16
	v_sub_f32_e32 v5, v5, v12
	v_sub_f32_e32 v12, v9, v12
	v_add_f32_e32 v13, v10, v4
	v_sub_f32_e32 v12, v16, v12
	v_sub_f32_e32 v14, v13, v10
	v_add_f32_e32 v5, v5, v12
	v_sub_f32_e32 v12, v13, v14
	v_add_f32_e32 v5, v13, v5
	v_sub_f32_e32 v10, v10, v12
	v_add_f32_e32 v12, v9, v5
	v_sub_f32_e32 v4, v4, v14
	v_sub_f32_e32 v9, v12, v9
	v_add_f32_e32 v4, v4, v10
	v_sub_f32_e32 v5, v5, v9
	v_add_f32_e32 v4, v4, v5
	s_mov_b32 s16, 0x7f800000
	v_add_f32_e32 v4, v12, v4
	v_cmp_neq_f32_e32 vcc, s16, v8
	s_mov_b32 s16, 0x33800000
	s_nop 0
	v_cndmask_b32_e32 v4, v193, v4, vcc
	v_cmp_lt_f32_e64 vcc, |v8|, s16
	s_nop 1
	v_cndmask_b32_e32 v4, v4, v8, vcc
	v_add_f32_e32 v4, v11, v4
	v_mul_f32_e64 v5, v4, -v3
	ds_bpermute_b32 v8, v104, v5
	v_cmp_nlt_f32_e32 vcc, s96, v2
	s_waitcnt lgkmcnt(0)
	v_fma_f32 v3, v4, -v3, v8
	v_cndmask_b32_e64 v3, v3, v5, s[58:59]
	ds_bpermute_b32 v4, v105, v3
	v_cndmask_b32_e32 v5, 0, v6, vcc
	v_cmp_ngt_f32_e32 vcc, s97, v2
	s_waitcnt lgkmcnt(0)
	v_add_f32_e32 v4, v3, v4
	v_cndmask_b32_e64 v3, v4, v3, s[56:57]
	ds_bpermute_b32 v4, v106, v3
	v_cndmask_b32_e32 v2, v193, v5, vcc
	v_add_f32_e32 v2, 1.0, v2
	v_div_scale_f32 v5, s[16:17], v2, v2, 1.0
	s_waitcnt lgkmcnt(0)
	v_add_f32_e32 v4, v3, v4
	v_cndmask_b32_e64 v3, v4, v3, s[74:75]
	ds_bpermute_b32 v4, v107, v3
	v_rcp_f32_e32 v6, v5
	v_div_scale_f32 v7, vcc, 1.0, v2, 1.0
	s_waitcnt lgkmcnt(0)
	v_add_f32_e32 v4, v3, v4
	v_cndmask_b32_e64 v3, v4, v3, s[76:77]
	ds_bpermute_b32 v4, v108, v3
	v_fma_f32 v8, -v5, v6, 1.0
	v_fmac_f32_e32 v6, v8, v6
	v_mul_f32_e32 v8, v7, v6
	v_fma_f32 v9, -v5, v8, v7
	s_waitcnt lgkmcnt(0)
	v_add_f32_e32 v4, v3, v4
	v_cndmask_b32_e64 v3, v4, v3, s[78:79]
	ds_bpermute_b32 v4, v109, v3
	v_fmac_f32_e32 v8, v9, v6
	v_fma_f32 v5, -v5, v8, v7
	v_div_fmas_f32 v5, v5, v6, v8
	v_div_fixup_f32 v2, v5, v2, 1.0
	s_waitcnt lgkmcnt(0)
	v_add_f32_e32 v4, v3, v4
	v_cndmask_b32_e64 v3, v4, v3, s[60:61]
	ds_write_b32 v117, v3
	ds_write_b32 v118, v2
